# single-active QK with 8 reads in flight; gate logits loaded at branch start; norm epilogue loads ahead of stores; P9 epilogue without canonicalising max
# speedup vs baseline: 1.0410x; 1.0048x over previous
; __device__ __forceinline__ float af_sigmoid(float x) { return 1.f / (1.f + __expf(-x)); }
; __device__ __forceinline__ void attn_fast(const Ptrs& P, LAS unsigned char* lds, int G, int bid) {
;     ...
;                 const h16* KB = Ub + (br == 1 ? OFF_KS : OFF_KW) + g * 128;
;                 const h16* VB = Ub + (br == 1 ? OFF_VS : OFF_VW) + g * 128;
;                 const int j_lo = br == 1 ? 0 : (qb >= 8 ? qb - 8 : 0);
;                 const int nt = qb - j_lo + 1;
;                 m[0] = m[1] = -1.0e30f; l[0] = l[1] = 0.f;
; #pragma unroll
;                 for (int ct = 0; ct < 2; ++ct)
; #pragma unroll
;                     for (int dt = 0; dt < 8; ++dt) o[ct][dt] = (f32x4){0.f, 0.f, 0.f, 0.f};
;                 AF_ISSUE(0, KB, VB, DINP, 64 * j_lo, true);
;                 if (nt > 1) AF_ISSUE(1, KB, VB, DINP, 64 * (j_lo + 1), true);
;                 if (nt > 2) AF_ISSUE(2, KB, VB, DINP, 64 * (j_lo + 2), true);
;     ...
;                     const size_t row = (size_t)b * SEQ + 64 * qb + 8 * w + 4 * ct + (fr_ >> 2);
;                     float lt = l[ct]; lt += __shfl_xor(lt, 16); lt += __shfl_xor(lt, 32);
;                     const float gg = af_sigmoid((float)U[row * DINP + OFF_GL + (4 * g + hh_) * 3 + br]);
.LBB0_578:
.LBB0_580:
	s_cmp_lt_i32 s17, 0
	s_cbranch_scc1 .LBB0_622
	v_lshrrev_b32_e32 v38, 2, v172
	v_and_or_b32 v42, v38, 3, s28
	v_and_or_b32 v38, v38, 3, s37
	v_and_or_b32 v40, v172, 3, s1
	v_mul_u32_u24_e32 v40, 3, v40
	v_lshlrev_b32_e32 v40, 1, v40
	v_mov_b32_e32 v41, 0
	v_mov_b32_e32 v39, s95
	v_mov_b64_e32 v[44:45], s[18:19]
	v_mad_u64_u32 v[44:45], s[8:9], v38, s86, v[44:45]
	v_mov_b32_e32 v2, v45
	v_mad_u64_u32 v[46:47], s[8:9], v39, s86, v[2:3]
	v_mov_b32_e32 v45, v46
	v_lshl_add_u64 v[44:45], v[44:45], 0, v[40:41]
	v_lshl_add_u64 v[44:45], s[52:53], 1, v[44:45]
	v_add_co_u32_e32 v44, vcc, s93, v44
	s_nop 1
	v_addc_co_u32_e32 v45, vcc, 0, v45, vcc
	global_load_ushort v254, v[44:45], off offset:3072
	v_mov_b64_e32 v[44:45], s[18:19]
	v_mad_u64_u32 v[44:45], s[8:9], v42, s86, v[44:45]
	v_mov_b32_e32 v2, v45
	v_mad_u64_u32 v[46:47], s[8:9], v39, s86, v[2:3]
	v_mov_b32_e32 v45, v46
	v_lshl_add_u64 v[44:45], v[44:45], 0, v[40:41]
	v_lshl_add_u64 v[44:45], s[52:53], 1, v[44:45]
	v_add_co_u32_e32 v44, vcc, s93, v44
	s_nop 1
	v_addc_co_u32_e32 v45, vcc, 0, v45, vcc
	global_load_ushort v255, v[44:45], off offset:3072
	v_mov_b32_e32 v4, v3
	v_mov_b32_e32 v5, v3
	v_mov_b32_e32 v2, v3
	v_mov_b64_e32 v[40:41], v[4:5]
	v_mov_b64_e32 v[44:45], v[4:5]
	v_mov_b64_e32 v[56:57], v[4:5]
	v_mov_b64_e32 v[60:61], v[4:5]
	v_mov_b64_e32 v[72:73], v[4:5]
	v_mov_b64_e32 v[80:81], v[4:5]
	v_mov_b64_e32 v[92:93], v[4:5]
	v_mov_b64_e32 v[100:101], v[4:5]
	v_mov_b64_e32 v[96:97], v[4:5]
	v_mov_b64_e32 v[88:89], v[4:5]
	v_mov_b64_e32 v[84:85], v[4:5]
	v_mov_b64_e32 v[76:77], v[4:5]
	v_mov_b64_e32 v[68:69], v[4:5]
	v_mov_b64_e32 v[64:65], v[4:5]
	v_mov_b64_e32 v[52:53], v[4:5]
	v_mov_b64_e32 v[48:49], v[4:5]
	s_add_i32 s22, s17, 1
	s_mov_b32 s23, 0
	v_mov_b32_e32 v217, 0xf149f2ca
	v_mov_b32_e32 v216, 0
	v_mov_b64_e32 v[38:39], v[2:3]
	v_mov_b64_e32 v[42:43], v[2:3]
	v_mov_b64_e32 v[54:55], v[2:3]
	v_mov_b64_e32 v[58:59], v[2:3]
	v_mov_b64_e32 v[70:71], v[2:3]
	v_mov_b64_e32 v[78:79], v[2:3]
	v_mov_b64_e32 v[90:91], v[2:3]
	v_mov_b64_e32 v[98:99], v[2:3]
	v_mov_b64_e32 v[94:95], v[2:3]
	v_mov_b64_e32 v[86:87], v[2:3]
	v_mov_b64_e32 v[82:83], v[2:3]
	v_mov_b64_e32 v[74:75], v[2:3]
	v_mov_b64_e32 v[66:67], v[2:3]
	v_mov_b64_e32 v[62:63], v[2:3]
	v_mov_b64_e32 v[50:51], v[2:3]
	v_mov_b64_e32 v[46:47], v[2:3]
	v_mov_b32_e32 v5, 0
	v_mov_b32_e32 v4, 0xf149f2ca
	s_mov_b32 s3, 0

; #define LAS __attribute__((address_space(3)))
; template <bool a0, bool a1> __device__ __forceinline__ void af_qk(const LAS unsigned char* kbuf, const unsigned (&kl)[4], const half8 (&qf)[2][4], f32x4 (&s)[2][4]) {
;     const LAS unsigned char* ka[4];
;     { int _ln; asm volatile("v_mov_b32 %0, %1" : "=v"(_ln) : "v"(kl[0]));
;       const int fr_ = _ln & 15, e_ = (_ln >> 4) ^ fr_;
; #pragma unroll
;       for (int ks = 0; ks < 4; ++ks) ka[ks] = kbuf + fr_ * 256 + ((e_ ^ (4 * ks)) << 4); }
;     half8 kf[2][4];
; #pragma unroll
;     for (int ks = 0; ks < 4; ++ks) kf[0][ks] = *(const LAS half8*)(ka[ks]);
; #pragma unroll
;     for (int kt = 0; kt < 4; ++kt) {
;         if (kt < 3) {
; #pragma unroll
;             for (int ks = 0; ks < 4; ++ks) kf[(kt + 1) & 1][ks] = *(const LAS half8*)(ka[ks] + (kt + 1) * 4096); }
;         s[0][kt] = (f32x4){0.f, 0.f, 0.f, 0.f}; s[1][kt] = (f32x4){0.f, 0.f, 0.f, 0.f};
; #pragma unroll
;         for (int ks = 0; ks < 4; ++ks) {
;             if (a0) s[0][kt] = __builtin_amdgcn_mfma_f32_16x16x32_f16(kf[kt & 1][ks], qf[0][ks], s[0][kt], 0, 0, 0);
;             if (a1) s[1][kt] = __builtin_amdgcn_mfma_f32_16x16x32_f16(kf[kt & 1][ks], qf[1][ks], s[1][kt], 0, 0, 0); }
;         __builtin_amdgcn_sched_barrier(0);
;     }
; }
; __device__ __forceinline__ void af_maskraw(f32x4 (&s)[4], int mbase, int mstep, int fq, int hi, int lo) {
; #pragma unroll
;     for (int kt = 0; kt < 4; ++kt)
; #pragma unroll
;         for (int jj = 0; jj < 4; ++jj) { const int met = mbase + mstep * (16 * kt + 4 * fq + jj); s[kt][jj] = (met <= hi && met > lo) ? s[kt][jj] : -3.0e38f; }
; }
.LBB0_594:
	s_cmp_eq_u32 s17, s3
	s_cselect_b64 s[6:7], -1, 0
	s_cmp_le_i32 s16, s97
	s_cselect_b64 s[60:61], -1, 0
	s_and_b64 s[60:61], s[12:13], s[60:61]
	s_or_b64 s[60:61], s[6:7], s[60:61]
	s_and_b32 s6, s23, 0x18000
	s_add_i32 s64, s6, 0
	s_and_b64 s[6:7], s[62:63], s[8:9]
	s_andn2_b64 vcc, exec, s[6:7]
	s_mov_b64 s[6:7], -1
	s_cbranch_vccz .LBB0_610
	s_xor_b64 s[62:63], s[62:63], -1
	s_and_b64 vcc, exec, s[62:63]
	s_cbranch_vccz .LBB0_603
	v_mov_b64_e32 v[132:133], v[48:49]
	v_mov_b64_e32 v[128:129], v[52:53]
	v_mov_b64_e32 v[124:125], v[64:65]
	v_mov_b64_e32 v[120:121], v[68:69]
	v_mov_b64_e32 v[116:117], v[76:77]
	v_mov_b64_e32 v[112:113], v[84:85]
	v_mov_b64_e32 v[108:109], v[88:89]
	v_mov_b64_e32 v[104:105], v[96:97]
	s_andn2_b64 vcc, exec, s[8:9]
	v_mov_b32_e32 v224, v4
	v_mov_b32_e32 v222, v5
	v_mov_b64_e32 v[130:131], v[46:47]
	v_mov_b64_e32 v[126:127], v[50:51]
	v_mov_b64_e32 v[122:123], v[62:63]
	v_mov_b64_e32 v[118:119], v[66:67]
	v_mov_b64_e32 v[114:115], v[74:75]
	v_mov_b64_e32 v[110:111], v[82:83]
	v_mov_b64_e32 v[106:107], v[86:87]
	v_mov_b64_e32 v[102:103], v[94:95]
	s_cbranch_vccnz .LBB0_602
	v_mov_b32 v118, v172
	s_nop 0
	v_and_b32_e32 v119, 15, v118
	v_lshl_add_u32 v122, v119, 8, s64
	v_lshlrev_b32_e32 v119, 4, v119
	v_bitop3_b32 v123, v119, v118, -16 bitop3:0x78
	v_add_u32_e32 v118, v122, v123
	v_xad_u32 v119, v123, 64, v122
	v_xad_u32 v120, v123, s77, v122
	v_xad_u32 v121, v123, s78, v122
	ds_read_b128 v[134:137], v118
	ds_read_b128 v[138:141], v119
	ds_read_b128 v[142:145], v120
	ds_read_b128 v[146:149], v121
	ds_read_b128 v[150:153], v118 offset:4096
	ds_read_b128 v[154:157], v119 offset:4096
	ds_read_b128 v[158:161], v120 offset:4096
	ds_read_b128 v[162:165], v121 offset:4096
	s_waitcnt lgkmcnt(4)
	v_mfma_f32_16x16x32_f16 v[114:117], v[134:137], v[22:25], 0
	v_mfma_f32_16x16x32_f16 v[114:117], v[138:141], v[26:29], v[114:117]
	v_mfma_f32_16x16x32_f16 v[114:117], v[142:145], v[30:33], v[114:117]
	v_mfma_f32_16x16x32_f16 v[114:117], v[146:149], v[34:37], v[114:117]
	ds_read_b128 v[134:137], v118 offset:8192
	ds_read_b128 v[138:141], v119 offset:8192
	ds_read_b128 v[142:145], v120 offset:8192
	ds_read_b128 v[146:149], v121 offset:8192
	s_waitcnt lgkmcnt(4)
	v_mfma_f32_16x16x32_f16 v[110:113], v[150:153], v[22:25], 0
	v_mfma_f32_16x16x32_f16 v[110:113], v[154:157], v[26:29], v[110:113]
	v_mfma_f32_16x16x32_f16 v[110:113], v[158:161], v[30:33], v[110:113]
	v_mfma_f32_16x16x32_f16 v[110:113], v[162:165], v[34:37], v[110:113]
	ds_read_b128 v[150:153], v118 offset:12288
	ds_read_b128 v[154:157], v119 offset:12288
	ds_read_b128 v[158:161], v120 offset:12288
	ds_read_b128 v[162:165], v121 offset:12288
	s_waitcnt lgkmcnt(4)
	v_mfma_f32_16x16x32_f16 v[106:109], v[134:137], v[22:25], 0
	v_mfma_f32_16x16x32_f16 v[106:109], v[138:141], v[26:29], v[106:109]
	v_mfma_f32_16x16x32_f16 v[106:109], v[142:145], v[30:33], v[106:109]
	v_mfma_f32_16x16x32_f16 v[106:109], v[146:149], v[34:37], v[106:109]
	s_waitcnt lgkmcnt(0)
	v_mfma_f32_16x16x32_f16 v[102:105], v[150:153], v[22:25], 0
	v_mfma_f32_16x16x32_f16 v[102:105], v[154:157], v[26:29], v[102:105]
	v_mfma_f32_16x16x32_f16 v[102:105], v[158:161], v[30:33], v[102:105]
	v_mfma_f32_16x16x32_f16 v[102:105], v[162:165], v[34:37], v[102:105]
	s_andn2_b64 vcc, exec, s[60:61]
	s_cbranch_vccnz .LBB0_599
	v_add_u32_e32 v118, s16, v173
	v_cmp_le_i32_e32 vcc, v118, v2
	v_cmp_gt_i32_e64 s[6:7], v118, v218
	s_and_b64 vcc, vcc, s[6:7]
	v_cndmask_b32_e32 v114, v202, v114, vcc
	v_cmp_lt_i32_e32 vcc, v118, v2
	v_cmp_ge_i32_e64 s[6:7], v118, v218
	s_and_b64 vcc, vcc, s[6:7]
	v_add_u32_e32 v119, 2, v118
	v_cndmask_b32_e32 v115, v202, v115, vcc
	v_cmp_le_i32_e32 vcc, v119, v2
	v_cmp_gt_i32_e64 s[6:7], v119, v218
	s_and_b64 vcc, vcc, s[6:7]
	v_add_u32_e32 v119, 3, v118
	v_cndmask_b32_e32 v116, v202, v116, vcc
	v_cmp_le_i32_e32 vcc, v119, v2
	v_cmp_gt_i32_e64 s[6:7], v119, v218
	s_and_b64 vcc, vcc, s[6:7]
	v_add_u32_e32 v119, 16, v118
	v_cndmask_b32_e32 v117, v202, v117, vcc
	v_cmp_le_i32_e32 vcc, v119, v2
	v_cmp_gt_i32_e64 s[6:7], v119, v218
	s_and_b64 vcc, vcc, s[6:7]
	v_add_u32_e32 v119, 17, v118
	v_cndmask_b32_e32 v110, v202, v110, vcc
	v_cmp_le_i32_e32 vcc, v119, v2
	v_cmp_gt_i32_e64 s[6:7], v119, v218
	s_and_b64 vcc, vcc, s[6:7]
	v_add_u32_e32 v119, 18, v118
	v_cndmask_b32_e32 v111, v202, v111, vcc
	v_cmp_le_i32_e32 vcc, v119, v2
	v_cmp_gt_i32_e64 s[6:7], v119, v218
	s_and_b64 vcc, vcc, s[6:7]
	v_add_u32_e32 v119, 19, v118
	v_cndmask_b32_e32 v112, v202, v112, vcc
	v_cmp_le_i32_e32 vcc, v119, v2
	v_cmp_gt_i32_e64 s[6:7], v119, v218
	s_and_b64 vcc, vcc, s[6:7]
	v_add_u32_e32 v119, 32, v118
	v_cndmask_b32_e32 v113, v202, v113, vcc
	v_cmp_le_i32_e32 vcc, v119, v2
	v_cmp_gt_i32_e64 s[6:7], v119, v218
	s_and_b64 vcc, vcc, s[6:7]
	v_add_u32_e32 v119, 33, v118
	v_cndmask_b32_e32 v106, v202, v106, vcc
	v_cmp_le_i32_e32 vcc, v119, v2
	v_cmp_gt_i32_e64 s[6:7], v119, v218
	s_and_b64 vcc, vcc, s[6:7]
	v_add_u32_e32 v119, 34, v118
	v_cndmask_b32_e32 v107, v202, v107, vcc
	v_cmp_le_i32_e32 vcc, v119, v2
	v_cmp_gt_i32_e64 s[6:7], v119, v218
	s_and_b64 vcc, vcc, s[6:7]
	v_add_u32_e32 v119, 35, v118
	v_cndmask_b32_e32 v108, v202, v108, vcc
	v_cmp_le_i32_e32 vcc, v119, v2
	v_cmp_gt_i32_e64 s[6:7], v119, v218
	s_and_b64 vcc, vcc, s[6:7]
	v_add_u32_e32 v119, 48, v118
	v_cndmask_b32_e32 v109, v202, v109, vcc
	v_cmp_le_i32_e32 vcc, v119, v2
	v_cmp_gt_i32_e64 s[6:7], v119, v218
	s_and_b64 vcc, vcc, s[6:7]
	v_add_u32_e32 v119, 49, v118
	v_cndmask_b32_e32 v102, v202, v102, vcc
	v_cmp_le_i32_e32 vcc, v119, v2
	v_cmp_gt_i32_e64 s[6:7], v119, v218
	s_and_b64 vcc, vcc, s[6:7]
	v_add_u32_e32 v119, 50, v118
	v_cndmask_b32_e32 v103, v202, v103, vcc
	v_cmp_le_i32_e32 vcc, v119, v2
	v_cmp_gt_i32_e64 s[6:7], v119, v218
	s_and_b64 vcc, vcc, s[6:7]
	v_add_u32_e32 v118, 51, v118
	v_cndmask_b32_e32 v104, v202, v104, vcc
	v_cmp_le_i32_e32 vcc, v118, v2
	v_cmp_gt_i32_e64 s[6:7], v118, v218
	s_and_b64 vcc, vcc, s[6:7]
	v_cndmask_b32_e32 v105, v202, v105, vcc

; #define LAS __attribute__((address_space(3)))
; template <bool a0, bool a1> __device__ __forceinline__ void af_qk(const LAS unsigned char* kbuf, const unsigned (&kl)[4], const half8 (&qf)[2][4], f32x4 (&s)[2][4]) {
;     const LAS unsigned char* ka[4];
;     { int _ln; asm volatile("v_mov_b32 %0, %1" : "=v"(_ln) : "v"(kl[0]));
;       const int fr_ = _ln & 15, e_ = (_ln >> 4) ^ fr_;
; #pragma unroll
;       for (int ks = 0; ks < 4; ++ks) ka[ks] = kbuf + fr_ * 256 + ((e_ ^ (4 * ks)) << 4); }
;     half8 kf[2][4];
; #pragma unroll
;     for (int ks = 0; ks < 4; ++ks) kf[0][ks] = *(const LAS half8*)(ka[ks]);
; #pragma unroll
;     for (int kt = 0; kt < 4; ++kt) {
;         if (kt < 3) {
; #pragma unroll
;             for (int ks = 0; ks < 4; ++ks) kf[(kt + 1) & 1][ks] = *(const LAS half8*)(ka[ks] + (kt + 1) * 4096); }
;         s[0][kt] = (f32x4){0.f, 0.f, 0.f, 0.f}; s[1][kt] = (f32x4){0.f, 0.f, 0.f, 0.f};
; #pragma unroll
;         for (int ks = 0; ks < 4; ++ks) {
;             if (a0) s[0][kt] = __builtin_amdgcn_mfma_f32_16x16x32_f16(kf[kt & 1][ks], qf[0][ks], s[0][kt], 0, 0, 0);
;             if (a1) s[1][kt] = __builtin_amdgcn_mfma_f32_16x16x32_f16(kf[kt & 1][ks], qf[1][ks], s[1][kt], 0, 0, 0); }
;         __builtin_amdgcn_sched_barrier(0);
;     }
; }
; __device__ __forceinline__ void af_maskraw(f32x4 (&s)[4], int mbase, int mstep, int fq, int hi, int lo) {
; #pragma unroll
;     for (int kt = 0; kt < 4; ++kt)
; #pragma unroll
;         for (int jj = 0; jj < 4; ++jj) { const int met = mbase + mstep * (16 * kt + 4 * fq + jj); s[kt][jj] = (met <= hi && met > lo) ? s[kt][jj] : -3.0e38f; }
; }
.LBB0_603:
	v_mov_b64_e32 v[136:137], v[100:101]
	v_mov_b64_e32 v[140:141], v[92:93]
	v_mov_b64_e32 v[144:145], v[80:81]
	v_mov_b64_e32 v[148:149], v[72:73]
	v_mov_b64_e32 v[152:153], v[60:61]
	v_mov_b64_e32 v[156:157], v[56:57]
	v_mov_b64_e32 v[160:161], v[44:45]
	v_mov_b64_e32 v[164:165], v[40:41]
	s_andn2_b64 vcc, exec, s[6:7]
	v_mov_b32_e32 v221, v217
	v_mov_b32_e32 v223, v216
	v_mov_b64_e32 v[134:135], v[98:99]
	v_mov_b64_e32 v[138:139], v[90:91]
	v_mov_b64_e32 v[142:143], v[78:79]
	v_mov_b64_e32 v[146:147], v[70:71]
	v_mov_b64_e32 v[150:151], v[58:59]
	v_mov_b64_e32 v[154:155], v[54:55]
	v_mov_b64_e32 v[158:159], v[42:43]
	v_mov_b64_e32 v[162:163], v[38:39]
	s_cbranch_vccnz .LBB0_609
	v_mov_b32 v114, v172
	s_nop 0
	v_and_b32_e32 v115, 15, v114
	v_lshl_add_u32 v118, v115, 8, s64
	v_lshlrev_b32_e32 v115, 4, v115
	v_bitop3_b32 v119, v115, v114, -16 bitop3:0x78
	v_add_u32_e32 v114, v118, v119
	v_xad_u32 v115, v119, 64, v118
	v_xad_u32 v116, v119, s77, v118
	v_xad_u32 v117, v119, s78, v118
	ds_read_b128 v[134:137], v114
	ds_read_b128 v[138:141], v115
	ds_read_b128 v[142:145], v116
	ds_read_b128 v[146:149], v117
	ds_read_b128 v[150:153], v114 offset:4096
	ds_read_b128 v[154:157], v115 offset:4096
	ds_read_b128 v[158:161], v116 offset:4096
	ds_read_b128 v[162:165], v117 offset:4096
	s_waitcnt lgkmcnt(4)
	v_mfma_f32_16x16x32_f16 v[122:125], v[134:137], v[6:9], 0
	v_mfma_f32_16x16x32_f16 v[122:125], v[138:141], v[10:13], v[122:125]
	v_mfma_f32_16x16x32_f16 v[122:125], v[142:145], v[14:17], v[122:125]
	v_mfma_f32_16x16x32_f16 v[122:125], v[146:149], v[18:21], v[122:125]
	ds_read_b128 v[134:137], v114 offset:8192
	ds_read_b128 v[138:141], v115 offset:8192
	ds_read_b128 v[142:145], v116 offset:8192
	ds_read_b128 v[146:149], v117 offset:8192
	s_waitcnt lgkmcnt(4)
	v_mfma_f32_16x16x32_f16 v[110:113], v[150:153], v[6:9], 0
	v_mfma_f32_16x16x32_f16 v[110:113], v[154:157], v[10:13], v[110:113]
	v_mfma_f32_16x16x32_f16 v[110:113], v[158:161], v[14:17], v[110:113]
	v_mfma_f32_16x16x32_f16 v[110:113], v[162:165], v[18:21], v[110:113]
	ds_read_b128 v[150:153], v114 offset:12288
	ds_read_b128 v[154:157], v115 offset:12288
	ds_read_b128 v[158:161], v116 offset:12288
	ds_read_b128 v[162:165], v117 offset:12288
	s_waitcnt lgkmcnt(4)
	v_mfma_f32_16x16x32_f16 v[106:109], v[134:137], v[6:9], 0
	v_mfma_f32_16x16x32_f16 v[106:109], v[138:141], v[10:13], v[106:109]
	v_mfma_f32_16x16x32_f16 v[106:109], v[142:145], v[14:17], v[106:109]
	v_mfma_f32_16x16x32_f16 v[106:109], v[146:149], v[18:21], v[106:109]
	s_waitcnt lgkmcnt(0)
	v_mfma_f32_16x16x32_f16 v[102:105], v[150:153], v[6:9], 0
	v_mfma_f32_16x16x32_f16 v[102:105], v[154:157], v[10:13], v[102:105]
	v_mfma_f32_16x16x32_f16 v[102:105], v[158:161], v[14:17], v[102:105]
	v_mfma_f32_16x16x32_f16 v[102:105], v[162:165], v[18:21], v[102:105]
	s_andn2_b64 vcc, exec, s[60:61]
	s_cbranch_vccnz .LBB0_606
	v_add_u32_e32 v114, s16, v173
	v_cmp_le_i32_e32 vcc, v114, v219
	v_cmp_gt_i32_e64 s[6:7], v114, v220
	s_and_b64 vcc, vcc, s[6:7]
	v_cndmask_b32_e32 v122, v202, v122, vcc
	v_cmp_lt_i32_e32 vcc, v114, v219
	v_cmp_ge_i32_e64 s[6:7], v114, v220
	s_and_b64 vcc, vcc, s[6:7]
	v_add_u32_e32 v115, 2, v114
	v_cndmask_b32_e32 v123, v202, v123, vcc
	v_cmp_le_i32_e32 vcc, v115, v219
	v_cmp_gt_i32_e64 s[6:7], v115, v220
	s_and_b64 vcc, vcc, s[6:7]
	v_add_u32_e32 v115, 3, v114
	v_cndmask_b32_e32 v124, v202, v124, vcc
	v_cmp_le_i32_e32 vcc, v115, v219
	v_cmp_gt_i32_e64 s[6:7], v115, v220
	s_and_b64 vcc, vcc, s[6:7]
	v_add_u32_e32 v115, 16, v114
	v_cndmask_b32_e32 v125, v202, v125, vcc
	v_cmp_le_i32_e32 vcc, v115, v219
	v_cmp_gt_i32_e64 s[6:7], v115, v220
	s_and_b64 vcc, vcc, s[6:7]
	v_add_u32_e32 v115, 17, v114
	v_cndmask_b32_e32 v110, v202, v110, vcc
	v_cmp_le_i32_e32 vcc, v115, v219
	v_cmp_gt_i32_e64 s[6:7], v115, v220
	s_and_b64 vcc, vcc, s[6:7]
	v_add_u32_e32 v115, 18, v114
	v_cndmask_b32_e32 v111, v202, v111, vcc
	v_cmp_le_i32_e32 vcc, v115, v219
	v_cmp_gt_i32_e64 s[6:7], v115, v220
	s_and_b64 vcc, vcc, s[6:7]
	v_add_u32_e32 v115, 19, v114
	v_cndmask_b32_e32 v112, v202, v112, vcc
	v_cmp_le_i32_e32 vcc, v115, v219
	v_cmp_gt_i32_e64 s[6:7], v115, v220
	s_and_b64 vcc, vcc, s[6:7]
	v_add_u32_e32 v115, 32, v114
	v_cndmask_b32_e32 v113, v202, v113, vcc
	v_cmp_le_i32_e32 vcc, v115, v219
	v_cmp_gt_i32_e64 s[6:7], v115, v220
	s_and_b64 vcc, vcc, s[6:7]
	v_add_u32_e32 v115, 33, v114
	v_cndmask_b32_e32 v106, v202, v106, vcc
	v_cmp_le_i32_e32 vcc, v115, v219
	v_cmp_gt_i32_e64 s[6:7], v115, v220
	s_and_b64 vcc, vcc, s[6:7]
	v_add_u32_e32 v115, 34, v114
	v_cndmask_b32_e32 v107, v202, v107, vcc
	v_cmp_le_i32_e32 vcc, v115, v219
	v_cmp_gt_i32_e64 s[6:7], v115, v220
	s_and_b64 vcc, vcc, s[6:7]
	v_add_u32_e32 v115, 35, v114
	v_cndmask_b32_e32 v108, v202, v108, vcc
	v_cmp_le_i32_e32 vcc, v115, v219
	v_cmp_gt_i32_e64 s[6:7], v115, v220
	s_and_b64 vcc, vcc, s[6:7]
	v_add_u32_e32 v115, 48, v114
	v_cndmask_b32_e32 v109, v202, v109, vcc
	v_cmp_le_i32_e32 vcc, v115, v219
	v_cmp_gt_i32_e64 s[6:7], v115, v220
	s_and_b64 vcc, vcc, s[6:7]
	v_add_u32_e32 v115, 49, v114
	v_cndmask_b32_e32 v102, v202, v102, vcc
	v_cmp_le_i32_e32 vcc, v115, v219
	v_cmp_gt_i32_e64 s[6:7], v115, v220
	s_and_b64 vcc, vcc, s[6:7]
	v_add_u32_e32 v115, 50, v114
	v_cndmask_b32_e32 v103, v202, v103, vcc
	v_cmp_le_i32_e32 vcc, v115, v219
	v_cmp_gt_i32_e64 s[6:7], v115, v220
	s_and_b64 vcc, vcc, s[6:7]
	v_add_u32_e32 v114, 51, v114
	v_cndmask_b32_e32 v104, v202, v104, vcc
	v_cmp_le_i32_e32 vcc, v114, v219
	v_cmp_gt_i32_e64 s[6:7], v114, v220
	s_and_b64 vcc, vcc, s[6:7]
	v_cndmask_b32_e32 v105, v202, v105, vcc

; #define LAS __attribute__((address_space(3)))
; template <bool a0, bool a1> __device__ __forceinline__ void af_qk(const LAS unsigned char* kbuf, const unsigned (&kl)[4], const half8 (&qf)[2][4], f32x4 (&s)[2][4]) {
;     const LAS unsigned char* ka[4];
;     { int _ln; asm volatile("v_mov_b32 %0, %1" : "=v"(_ln) : "v"(kl[0]));
;       const int fr_ = _ln & 15, e_ = (_ln >> 4) ^ fr_;
; #pragma unroll
;       for (int ks = 0; ks < 4; ++ks) ka[ks] = kbuf + fr_ * 256 + ((e_ ^ (4 * ks)) << 4); }
;     half8 kf[2][4];
; #pragma unroll
;     for (int ks = 0; ks < 4; ++ks) kf[0][ks] = *(const LAS half8*)(ka[ks]);
; #pragma unroll
;     for (int kt = 0; kt < 4; ++kt) {
;         if (kt < 3) {
; #pragma unroll
;             for (int ks = 0; ks < 4; ++ks) kf[(kt + 1) & 1][ks] = *(const LAS half8*)(ka[ks] + (kt + 1) * 4096); }
;         s[0][kt] = (f32x4){0.f, 0.f, 0.f, 0.f}; s[1][kt] = (f32x4){0.f, 0.f, 0.f, 0.f};
; #pragma unroll
;         for (int ks = 0; ks < 4; ++ks) {
;             if (a0) s[0][kt] = __builtin_amdgcn_mfma_f32_16x16x32_f16(kf[kt & 1][ks], qf[0][ks], s[0][kt], 0, 0, 0);
;             if (a1) s[1][kt] = __builtin_amdgcn_mfma_f32_16x16x32_f16(kf[kt & 1][ks], qf[1][ks], s[1][kt], 0, 0, 0); }
;         __builtin_amdgcn_sched_barrier(0);
;     }
; }
; __device__ __forceinline__ void af_maskraw(f32x4 (&s)[4], int mbase, int mstep, int fq, int hi, int lo) {
; #pragma unroll
;     for (int kt = 0; kt < 4; ++kt)
; #pragma unroll
;         for (int jj = 0; jj < 4; ++jj) { const int met = mbase + mstep * (16 * kt + 4 * fq + jj); s[kt][jj] = (met <= hi && met > lo) ? s[kt][jj] : -3.0e38f; }
; }
.Lu2_594:
	s_cmp_eq_u32 s17, s3
	s_cselect_b64 s[6:7], -1, 0
	s_cmp_le_i32 s16, s97
	s_cselect_b64 s[60:61], -1, 0
	s_and_b64 s[60:61], s[12:13], s[60:61]
	s_or_b64 s[60:61], s[6:7], s[60:61]
	s_and_b32 s6, s23, 0x18000
	s_add_i32 s64, s6, 0
	s_and_b64 s[6:7], s[62:63], s[8:9]
	s_andn2_b64 vcc, exec, s[6:7]
	s_mov_b64 s[6:7], -1
	s_cbranch_vccz .Lu2_610
	s_xor_b64 s[62:63], s[62:63], -1
	s_and_b64 vcc, exec, s[62:63]
	s_cbranch_vccz .Lu2_603
	v_mov_b64_e32 v[48:49], v[132:133]
	v_mov_b64_e32 v[52:53], v[128:129]
	v_mov_b64_e32 v[64:65], v[124:125]
	v_mov_b64_e32 v[68:69], v[120:121]
	v_mov_b64_e32 v[76:77], v[116:117]
	v_mov_b64_e32 v[84:85], v[112:113]
	v_mov_b64_e32 v[88:89], v[108:109]
	v_mov_b64_e32 v[96:97], v[104:105]
	s_andn2_b64 vcc, exec, s[8:9]
	v_mov_b32_e32 v224, v4
	v_mov_b32_e32 v222, v5
	v_mov_b64_e32 v[46:47], v[130:131]
	v_mov_b64_e32 v[50:51], v[126:127]
	v_mov_b64_e32 v[62:63], v[122:123]
	v_mov_b64_e32 v[66:67], v[118:119]
	v_mov_b64_e32 v[74:75], v[114:115]
	v_mov_b64_e32 v[82:83], v[110:111]
	v_mov_b64_e32 v[86:87], v[106:107]
	v_mov_b64_e32 v[94:95], v[102:103]
	s_cbranch_vccnz .Lu2_602
	v_mov_b32 v66, v172
	s_nop 0
	v_and_b32_e32 v67, 15, v66
	v_lshl_add_u32 v62, v67, 8, s64
	v_lshlrev_b32_e32 v67, 4, v67
	v_bitop3_b32 v63, v67, v66, -16 bitop3:0x78
	v_add_u32_e32 v66, v62, v63
	v_xad_u32 v67, v63, 64, v62
	v_xad_u32 v68, v63, s77, v62
	v_xad_u32 v69, v63, s78, v62
	ds_read_b128 v[98:101], v66
	ds_read_b128 v[90:93], v67
	ds_read_b128 v[78:81], v68
	ds_read_b128 v[70:73], v69
	ds_read_b128 v[58:61], v66 offset:4096
	ds_read_b128 v[54:57], v67 offset:4096
	ds_read_b128 v[42:45], v68 offset:4096
	ds_read_b128 v[38:41], v69 offset:4096
	s_waitcnt lgkmcnt(4)
	v_mfma_f32_16x16x32_f16 v[74:77], v[98:101], v[22:25], 0
	v_mfma_f32_16x16x32_f16 v[74:77], v[90:93], v[26:29], v[74:77]
	v_mfma_f32_16x16x32_f16 v[74:77], v[78:81], v[30:33], v[74:77]
	v_mfma_f32_16x16x32_f16 v[74:77], v[70:73], v[34:37], v[74:77]
	ds_read_b128 v[98:101], v66 offset:8192
	ds_read_b128 v[90:93], v67 offset:8192
	ds_read_b128 v[78:81], v68 offset:8192
	ds_read_b128 v[70:73], v69 offset:8192
	s_waitcnt lgkmcnt(4)
	v_mfma_f32_16x16x32_f16 v[82:85], v[58:61], v[22:25], 0
	v_mfma_f32_16x16x32_f16 v[82:85], v[54:57], v[26:29], v[82:85]
	v_mfma_f32_16x16x32_f16 v[82:85], v[42:45], v[30:33], v[82:85]
	v_mfma_f32_16x16x32_f16 v[82:85], v[38:41], v[34:37], v[82:85]
	ds_read_b128 v[58:61], v66 offset:12288
	ds_read_b128 v[54:57], v67 offset:12288
	ds_read_b128 v[42:45], v68 offset:12288
	ds_read_b128 v[38:41], v69 offset:12288
	s_waitcnt lgkmcnt(4)
	v_mfma_f32_16x16x32_f16 v[86:89], v[98:101], v[22:25], 0
	v_mfma_f32_16x16x32_f16 v[86:89], v[90:93], v[26:29], v[86:89]
	v_mfma_f32_16x16x32_f16 v[86:89], v[78:81], v[30:33], v[86:89]
	v_mfma_f32_16x16x32_f16 v[86:89], v[70:73], v[34:37], v[86:89]
	s_waitcnt lgkmcnt(0)
	v_mfma_f32_16x16x32_f16 v[94:97], v[58:61], v[22:25], 0
	v_mfma_f32_16x16x32_f16 v[94:97], v[54:57], v[26:29], v[94:97]
	v_mfma_f32_16x16x32_f16 v[94:97], v[42:45], v[30:33], v[94:97]
	v_mfma_f32_16x16x32_f16 v[94:97], v[38:41], v[34:37], v[94:97]
	s_andn2_b64 vcc, exec, s[60:61]
	s_cbranch_vccnz .Lu2_599
	v_add_u32_e32 v66, s16, v173
	v_cmp_le_i32_e32 vcc, v66, v2
	v_cmp_gt_i32_e64 s[6:7], v66, v218
	s_and_b64 vcc, vcc, s[6:7]
	v_cndmask_b32_e32 v74, v202, v74, vcc
	v_cmp_lt_i32_e32 vcc, v66, v2
	v_cmp_ge_i32_e64 s[6:7], v66, v218
	s_and_b64 vcc, vcc, s[6:7]
	v_add_u32_e32 v67, 2, v66
	v_cndmask_b32_e32 v75, v202, v75, vcc
	v_cmp_le_i32_e32 vcc, v67, v2
	v_cmp_gt_i32_e64 s[6:7], v67, v218
	s_and_b64 vcc, vcc, s[6:7]
	v_add_u32_e32 v67, 3, v66
	v_cndmask_b32_e32 v76, v202, v76, vcc
	v_cmp_le_i32_e32 vcc, v67, v2
	v_cmp_gt_i32_e64 s[6:7], v67, v218
	s_and_b64 vcc, vcc, s[6:7]
	v_add_u32_e32 v67, 16, v66
	v_cndmask_b32_e32 v77, v202, v77, vcc
	v_cmp_le_i32_e32 vcc, v67, v2
	v_cmp_gt_i32_e64 s[6:7], v67, v218
	s_and_b64 vcc, vcc, s[6:7]
	v_add_u32_e32 v67, 17, v66
	v_cndmask_b32_e32 v82, v202, v82, vcc
	v_cmp_le_i32_e32 vcc, v67, v2
	v_cmp_gt_i32_e64 s[6:7], v67, v218
	s_and_b64 vcc, vcc, s[6:7]
	v_add_u32_e32 v67, 18, v66
	v_cndmask_b32_e32 v83, v202, v83, vcc
	v_cmp_le_i32_e32 vcc, v67, v2
	v_cmp_gt_i32_e64 s[6:7], v67, v218
	s_and_b64 vcc, vcc, s[6:7]
	v_add_u32_e32 v67, 19, v66
	v_cndmask_b32_e32 v84, v202, v84, vcc
	v_cmp_le_i32_e32 vcc, v67, v2
	v_cmp_gt_i32_e64 s[6:7], v67, v218
	s_and_b64 vcc, vcc, s[6:7]
	v_add_u32_e32 v67, 32, v66
	v_cndmask_b32_e32 v85, v202, v85, vcc
	v_cmp_le_i32_e32 vcc, v67, v2
	v_cmp_gt_i32_e64 s[6:7], v67, v218
	s_and_b64 vcc, vcc, s[6:7]
	v_add_u32_e32 v67, 33, v66
	v_cndmask_b32_e32 v86, v202, v86, vcc
	v_cmp_le_i32_e32 vcc, v67, v2
	v_cmp_gt_i32_e64 s[6:7], v67, v218
	s_and_b64 vcc, vcc, s[6:7]
	v_add_u32_e32 v67, 34, v66
	v_cndmask_b32_e32 v87, v202, v87, vcc
	v_cmp_le_i32_e32 vcc, v67, v2
	v_cmp_gt_i32_e64 s[6:7], v67, v218
	s_and_b64 vcc, vcc, s[6:7]
	v_add_u32_e32 v67, 35, v66
	v_cndmask_b32_e32 v88, v202, v88, vcc
	v_cmp_le_i32_e32 vcc, v67, v2
	v_cmp_gt_i32_e64 s[6:7], v67, v218
	s_and_b64 vcc, vcc, s[6:7]
	v_add_u32_e32 v67, 48, v66
	v_cndmask_b32_e32 v89, v202, v89, vcc
	v_cmp_le_i32_e32 vcc, v67, v2
	v_cmp_gt_i32_e64 s[6:7], v67, v218
	s_and_b64 vcc, vcc, s[6:7]
	v_add_u32_e32 v67, 49, v66
	v_cndmask_b32_e32 v94, v202, v94, vcc
	v_cmp_le_i32_e32 vcc, v67, v2
	v_cmp_gt_i32_e64 s[6:7], v67, v218
	s_and_b64 vcc, vcc, s[6:7]
	v_add_u32_e32 v67, 50, v66
	v_cndmask_b32_e32 v95, v202, v95, vcc
	v_cmp_le_i32_e32 vcc, v67, v2
	v_cmp_gt_i32_e64 s[6:7], v67, v218
	s_and_b64 vcc, vcc, s[6:7]
	v_add_u32_e32 v66, 51, v66
	v_cndmask_b32_e32 v96, v202, v96, vcc
	v_cmp_le_i32_e32 vcc, v66, v2
	v_cmp_gt_i32_e64 s[6:7], v66, v218
	s_and_b64 vcc, vcc, s[6:7]
	v_cndmask_b32_e32 v97, v202, v97, vcc

; #define LAS __attribute__((address_space(3)))
; template <bool a0, bool a1> __device__ __forceinline__ void af_qk(const LAS unsigned char* kbuf, const unsigned (&kl)[4], const half8 (&qf)[2][4], f32x4 (&s)[2][4]) {
;     const LAS unsigned char* ka[4];
;     { int _ln; asm volatile("v_mov_b32 %0, %1" : "=v"(_ln) : "v"(kl[0]));
;       const int fr_ = _ln & 15, e_ = (_ln >> 4) ^ fr_;
; #pragma unroll
;       for (int ks = 0; ks < 4; ++ks) ka[ks] = kbuf + fr_ * 256 + ((e_ ^ (4 * ks)) << 4); }
;     half8 kf[2][4];
; #pragma unroll
;     for (int ks = 0; ks < 4; ++ks) kf[0][ks] = *(const LAS half8*)(ka[ks]);
; #pragma unroll
;     for (int kt = 0; kt < 4; ++kt) {
;         if (kt < 3) {
; #pragma unroll
;             for (int ks = 0; ks < 4; ++ks) kf[(kt + 1) & 1][ks] = *(const LAS half8*)(ka[ks] + (kt + 1) * 4096); }
;         s[0][kt] = (f32x4){0.f, 0.f, 0.f, 0.f}; s[1][kt] = (f32x4){0.f, 0.f, 0.f, 0.f};
; #pragma unroll
;         for (int ks = 0; ks < 4; ++ks) {
;             if (a0) s[0][kt] = __builtin_amdgcn_mfma_f32_16x16x32_f16(kf[kt & 1][ks], qf[0][ks], s[0][kt], 0, 0, 0);
;             if (a1) s[1][kt] = __builtin_amdgcn_mfma_f32_16x16x32_f16(kf[kt & 1][ks], qf[1][ks], s[1][kt], 0, 0, 0); }
;         __builtin_amdgcn_sched_barrier(0);
;     }
; }
; __device__ __forceinline__ void af_maskraw(f32x4 (&s)[4], int mbase, int mstep, int fq, int hi, int lo) {
; #pragma unroll
;     for (int kt = 0; kt < 4; ++kt)
; #pragma unroll
;         for (int jj = 0; jj < 4; ++jj) { const int met = mbase + mstep * (16 * kt + 4 * fq + jj); s[kt][jj] = (met <= hi && met > lo) ? s[kt][jj] : -3.0e38f; }
; }
.Lu2_603:
	v_mov_b64_e32 v[100:101], v[136:137]
	v_mov_b64_e32 v[92:93], v[140:141]
	v_mov_b64_e32 v[80:81], v[144:145]
	v_mov_b64_e32 v[72:73], v[148:149]
	v_mov_b64_e32 v[60:61], v[152:153]
	v_mov_b64_e32 v[56:57], v[156:157]
	v_mov_b64_e32 v[44:45], v[160:161]
	v_mov_b64_e32 v[40:41], v[164:165]
	s_andn2_b64 vcc, exec, s[6:7]
	v_mov_b32_e32 v221, v217
	v_mov_b32_e32 v223, v216
	v_mov_b64_e32 v[98:99], v[134:135]
	v_mov_b64_e32 v[90:91], v[138:139]
	v_mov_b64_e32 v[78:79], v[142:143]
	v_mov_b64_e32 v[70:71], v[146:147]
	v_mov_b64_e32 v[58:59], v[150:151]
	v_mov_b64_e32 v[54:55], v[154:155]
	v_mov_b64_e32 v[42:43], v[158:159]
	v_mov_b64_e32 v[38:39], v[162:163]
	s_cbranch_vccnz .Lu2_609
	v_mov_b32 v74, v172
	s_nop 0
	v_and_b32_e32 v75, 15, v74
	v_lshl_add_u32 v66, v75, 8, s64
	v_lshlrev_b32_e32 v75, 4, v75
	v_bitop3_b32 v67, v75, v74, -16 bitop3:0x78
	v_add_u32_e32 v74, v66, v67
	v_xad_u32 v75, v67, 64, v66
	v_xad_u32 v76, v67, s77, v66
	v_xad_u32 v77, v67, s78, v66
	ds_read_b128 v[98:101], v74
	ds_read_b128 v[90:93], v75
	ds_read_b128 v[78:81], v76
	ds_read_b128 v[70:73], v77
	ds_read_b128 v[58:61], v74 offset:4096
	ds_read_b128 v[54:57], v75 offset:4096
	ds_read_b128 v[42:45], v76 offset:4096
	ds_read_b128 v[38:41], v77 offset:4096
	s_waitcnt lgkmcnt(4)
	v_mfma_f32_16x16x32_f16 v[62:65], v[98:101], v[6:9], 0
	v_mfma_f32_16x16x32_f16 v[62:65], v[90:93], v[10:13], v[62:65]
	v_mfma_f32_16x16x32_f16 v[62:65], v[78:81], v[14:17], v[62:65]
	v_mfma_f32_16x16x32_f16 v[62:65], v[70:73], v[18:21], v[62:65]
	ds_read_b128 v[98:101], v74 offset:8192
	ds_read_b128 v[90:93], v75 offset:8192
	ds_read_b128 v[78:81], v76 offset:8192
	ds_read_b128 v[70:73], v77 offset:8192
	s_waitcnt lgkmcnt(4)
	v_mfma_f32_16x16x32_f16 v[82:85], v[58:61], v[6:9], 0
	v_mfma_f32_16x16x32_f16 v[82:85], v[54:57], v[10:13], v[82:85]
	v_mfma_f32_16x16x32_f16 v[82:85], v[42:45], v[14:17], v[82:85]
	v_mfma_f32_16x16x32_f16 v[82:85], v[38:41], v[18:21], v[82:85]
	ds_read_b128 v[58:61], v74 offset:12288
	ds_read_b128 v[54:57], v75 offset:12288
	ds_read_b128 v[42:45], v76 offset:12288
	ds_read_b128 v[38:41], v77 offset:12288
	s_waitcnt lgkmcnt(4)
	v_mfma_f32_16x16x32_f16 v[86:89], v[98:101], v[6:9], 0
	v_mfma_f32_16x16x32_f16 v[86:89], v[90:93], v[10:13], v[86:89]
	v_mfma_f32_16x16x32_f16 v[86:89], v[78:81], v[14:17], v[86:89]
	v_mfma_f32_16x16x32_f16 v[86:89], v[70:73], v[18:21], v[86:89]
	s_waitcnt lgkmcnt(0)
	v_mfma_f32_16x16x32_f16 v[94:97], v[58:61], v[6:9], 0
	v_mfma_f32_16x16x32_f16 v[94:97], v[54:57], v[10:13], v[94:97]
	v_mfma_f32_16x16x32_f16 v[94:97], v[42:45], v[14:17], v[94:97]
	v_mfma_f32_16x16x32_f16 v[94:97], v[38:41], v[18:21], v[94:97]
	s_andn2_b64 vcc, exec, s[60:61]
	s_cbranch_vccnz .Lu2_606
	v_add_u32_e32 v74, s16, v173
	v_cmp_le_i32_e32 vcc, v74, v219
	v_cmp_gt_i32_e64 s[6:7], v74, v220
	s_and_b64 vcc, vcc, s[6:7]
	v_cndmask_b32_e32 v62, v202, v62, vcc
	v_cmp_lt_i32_e32 vcc, v74, v219
	v_cmp_ge_i32_e64 s[6:7], v74, v220
	s_and_b64 vcc, vcc, s[6:7]
	v_add_u32_e32 v75, 2, v74
	v_cndmask_b32_e32 v63, v202, v63, vcc
	v_cmp_le_i32_e32 vcc, v75, v219
	v_cmp_gt_i32_e64 s[6:7], v75, v220
	s_and_b64 vcc, vcc, s[6:7]
	v_add_u32_e32 v75, 3, v74
	v_cndmask_b32_e32 v64, v202, v64, vcc
	v_cmp_le_i32_e32 vcc, v75, v219
	v_cmp_gt_i32_e64 s[6:7], v75, v220
	s_and_b64 vcc, vcc, s[6:7]
	v_add_u32_e32 v75, 16, v74
	v_cndmask_b32_e32 v65, v202, v65, vcc
	v_cmp_le_i32_e32 vcc, v75, v219
	v_cmp_gt_i32_e64 s[6:7], v75, v220
	s_and_b64 vcc, vcc, s[6:7]
	v_add_u32_e32 v75, 17, v74
	v_cndmask_b32_e32 v82, v202, v82, vcc
	v_cmp_le_i32_e32 vcc, v75, v219
	v_cmp_gt_i32_e64 s[6:7], v75, v220
	s_and_b64 vcc, vcc, s[6:7]
	v_add_u32_e32 v75, 18, v74
	v_cndmask_b32_e32 v83, v202, v83, vcc
	v_cmp_le_i32_e32 vcc, v75, v219
	v_cmp_gt_i32_e64 s[6:7], v75, v220
	s_and_b64 vcc, vcc, s[6:7]
	v_add_u32_e32 v75, 19, v74
	v_cndmask_b32_e32 v84, v202, v84, vcc
	v_cmp_le_i32_e32 vcc, v75, v219
	v_cmp_gt_i32_e64 s[6:7], v75, v220
	s_and_b64 vcc, vcc, s[6:7]
	v_add_u32_e32 v75, 32, v74
	v_cndmask_b32_e32 v85, v202, v85, vcc
	v_cmp_le_i32_e32 vcc, v75, v219
	v_cmp_gt_i32_e64 s[6:7], v75, v220
	s_and_b64 vcc, vcc, s[6:7]
	v_add_u32_e32 v75, 33, v74
	v_cndmask_b32_e32 v86, v202, v86, vcc
	v_cmp_le_i32_e32 vcc, v75, v219
	v_cmp_gt_i32_e64 s[6:7], v75, v220
	s_and_b64 vcc, vcc, s[6:7]
	v_add_u32_e32 v75, 34, v74
	v_cndmask_b32_e32 v87, v202, v87, vcc
	v_cmp_le_i32_e32 vcc, v75, v219
	v_cmp_gt_i32_e64 s[6:7], v75, v220
	s_and_b64 vcc, vcc, s[6:7]
	v_add_u32_e32 v75, 35, v74
	v_cndmask_b32_e32 v88, v202, v88, vcc
	v_cmp_le_i32_e32 vcc, v75, v219
	v_cmp_gt_i32_e64 s[6:7], v75, v220
	s_and_b64 vcc, vcc, s[6:7]
	v_add_u32_e32 v75, 48, v74
	v_cndmask_b32_e32 v89, v202, v89, vcc
	v_cmp_le_i32_e32 vcc, v75, v219
	v_cmp_gt_i32_e64 s[6:7], v75, v220
	s_and_b64 vcc, vcc, s[6:7]
	v_add_u32_e32 v75, 49, v74
	v_cndmask_b32_e32 v94, v202, v94, vcc
	v_cmp_le_i32_e32 vcc, v75, v219
	v_cmp_gt_i32_e64 s[6:7], v75, v220
	s_and_b64 vcc, vcc, s[6:7]
	v_add_u32_e32 v75, 50, v74
	v_cndmask_b32_e32 v95, v202, v95, vcc
	v_cmp_le_i32_e32 vcc, v75, v219
	v_cmp_gt_i32_e64 s[6:7], v75, v220
	s_and_b64 vcc, vcc, s[6:7]
	v_add_u32_e32 v74, 51, v74
	v_cndmask_b32_e32 v96, v202, v96, vcc
	v_cmp_le_i32_e32 vcc, v74, v219
	v_cmp_gt_i32_e64 s[6:7], v74, v220
	s_and_b64 vcc, vcc, s[6:7]
	v_cndmask_b32_e32 v97, v202, v97, vcc

; __device__ __forceinline__ void af_write(h16* Y, size_t row, int colbase, const f32x4 (&o)[8], float sc, bool accumulate) {
; #pragma unroll
;     for (int dt = 0; dt < 8; ++dt) { h16* p = Y + row * 1024 + colbase + 16 * dt; f32x4 v = o[dt] * sc;
;         if (accumulate) { const half4 h = *(const half4*)p; v += (f32x4){(float)h[0], (float)h[1], (float)h[2], (float)h[3]}; }
;         half4 hv; hv[0] = (h16)v[0]; hv[1] = (h16)v[1]; hv[2] = (h16)v[2]; hv[3] = (h16)v[3]; *(half4*)p = hv; }
; }
; __device__ __forceinline__ float af_sigmoid(float x) { return 1.f / (1.f + __expf(-x)); }
; __device__ __forceinline__ void attn_fast(const Ptrs& P, LAS unsigned char* lds, int G, int bid) {
;     ...
;                 for (int ct = 0; ct < 2; ++ct) { int _ln; asm volatile("v_mov_b32 %0, %1" : "=v"(_ln) : "v"(lane));
;                     const int fr_ = _ln & 15, fq_ = _ln >> 4, hh_ = fr_ & 3;
;                     const size_t row = (size_t)b * SEQ + 64 * qb + 8 * w + 4 * ct + (fr_ >> 2);
;                     float lt = l[ct]; lt += __shfl_xor(lt, 16); lt += __shfl_xor(lt, 32);
;                     const float gg = af_sigmoid((float)U[row * DINP + OFF_GL + (4 * g + hh_) * 3 + br]);
;                     af_write(Y, row, (4 * g + hh_) * 128 + 4 * fq_, o[ct], lt > 0.f ? 64.f * gg / lt : 0.f, true); }
.LBB0_623:
	ds_bpermute_b32 v2, v167, v223
	v_mov_b32 v5, v172
	v_mov_b32_e32 v39, s95
	v_lshrrev_b32_e32 v38, 2, v5
	v_mov_b32_e32 v4, 0
	s_waitcnt lgkmcnt(0)
	v_add_f32_e32 v2, v223, v2
	ds_bpermute_b32 v41, v207, v2
	v_and_or_b32 v40, v5, 3, s1
	v_and_or_b32 v38, v38, 3, s37
	s_waitcnt lgkmcnt(0)
	v_add_f32_e32 v41, v2, v41
	v_cmp_lt_f32_e32 vcc, 0, v41
	v_mov_b32_e32 v2, 0
	s_and_saveexec_b64 s[6:7], vcc
	s_cbranch_execz .LBB0_625
	v_mov_b32_e32 v2, v254
	v_cvt_f32_f16_e32 v2, v2
	v_mul_f32_e32 v2, 0xbfb8aa3b, v2
	v_exp_f32_e32 v2, v2
	s_nop 0
	v_add_f32_e32 v2, 1.0, v2
	v_div_scale_f32 v42, s[8:9], v2, v2, 1.0
	v_rcp_f32_e32 v43, v42
	v_div_scale_f32 v44, vcc, 1.0, v2, 1.0
	v_fma_f32 v45, -v42, v43, 1.0
	v_fmac_f32_e32 v43, v45, v43
	v_mul_f32_e32 v45, v44, v43
	v_fma_f32 v46, -v42, v45, v44
	v_fmac_f32_e32 v45, v46, v43
	v_fma_f32 v42, -v42, v45, v44
	v_div_fmas_f32 v42, v42, v43, v45
	v_div_fixup_f32 v2, v42, v2, 1.0
	v_mul_f32_e32 v2, 0x42800000, v2
	v_div_scale_f32 v42, s[8:9], v41, v41, v2
	v_rcp_f32_e32 v43, v42
	v_div_scale_f32 v44, vcc, v2, v41, v2
	v_fma_f32 v45, -v42, v43, 1.0
	v_fmac_f32_e32 v43, v45, v43
	v_mul_f32_e32 v45, v44, v43
	v_fma_f32 v46, -v42, v45, v44
	v_fmac_f32_e32 v45, v46, v43
	v_fma_f32 v42, -v42, v45, v44
	v_div_fmas_f32 v42, v42, v43, v45
	v_div_fixup_f32 v2, v42, v41, v2
; __device__ __forceinline__ float af_sigmoid(float x) { return 1.f / (1.f + __expf(-x)); }
; __device__ __forceinline__ void af_write(h16* Y, size_t row, int colbase, const f32x4 (&o)[8], float sc, bool accumulate) {
; #pragma unroll
;     for (int dt = 0; dt < 8; ++dt) { h16* p = Y + row * 1024 + colbase + 16 * dt; f32x4 v = o[dt] * sc;
;         if (accumulate) { const half4 h = *(const half4*)p; v += (f32x4){(float)h[0], (float)h[1], (float)h[2], (float)h[3]}; }
;         half4 hv; hv[0] = (h16)v[0]; hv[1] = (h16)v[1]; hv[2] = (h16)v[2]; hv[3] = (h16)v[3]; *(half4*)p = hv; }
; }
; __device__ __forceinline__ void attn_fast(const Ptrs& P, LAS unsigned char* lds, int G, int bid) {
;     ...
;                 for (int ct = 0; ct < 2; ++ct) { int _ln; asm volatile("v_mov_b32 %0, %1" : "=v"(_ln) : "v"(lane));
;                     const int fr_ = _ln & 15, fq_ = _ln >> 4, hh_ = fr_ & 3;
;                     const size_t row = (size_t)b * SEQ + 64 * qb + 8 * w + 4 * ct + (fr_ >> 2);
;                     float lt = l[ct]; lt += __shfl_xor(lt, 16); lt += __shfl_xor(lt, 32);
;                     const float gg = af_sigmoid((float)U[row * DINP + OFF_GL + (4 * g + hh_) * 3 + br]);
;                     af_write(Y, row, (4 * g + hh_) * 128 + 4 * fq_, o[ct], lt > 0.f ? 64.f * gg / lt : 0.f, true); }
.LBB0_625:
	s_or_b64 exec, exec, s[6:7]
	v_ashrrev_i32_e32 v5, 2, v5
	v_and_b32_e32 v5, -4, v5
	v_lshl_add_u32 v40, v40, 7, v5
	v_lshlrev_b64 v[38:39], 11, v[38:39]
	v_lshl_add_u64 v[38:39], s[20:21], 0, v[38:39]
	v_ashrrev_i32_e32 v41, 31, v40
	v_lshl_add_u64 v[38:39], v[40:41], 1, v[38:39]
	global_load_dwordx2 v[40:41], v[38:39], off
	global_load_dwordx2 v[44:45], v[38:39], off offset:32
	global_load_dwordx2 v[46:47], v[38:39], off offset:64
	global_load_dwordx2 v[48:49], v[38:39], off offset:96
	global_load_dwordx2 v[50:51], v[38:39], off offset:128
	global_load_dwordx2 v[52:53], v[38:39], off offset:160
	global_load_dwordx2 v[54:55], v[38:39], off offset:192
	global_load_dwordx2 v[56:57], v[38:39], off offset:224
	ds_bpermute_b32 v5, v167, v222
	v_mov_b32_e32 v43, s95
	s_waitcnt lgkmcnt(0)
	v_add_f32_e32 v74, v222, v5
	ds_bpermute_b32 v75, v207, v74
	s_waitcnt vmcnt(0)
	v_cvt_f32_f16_e32 v58, v40
	v_cvt_f32_f16_sdwa v59, v40 dst_sel:DWORD dst_unused:UNUSED_PAD src0_sel:WORD_1
	v_cvt_f32_f16_e32 v40, v41
	v_cvt_f32_f16_sdwa v41, v41 dst_sel:DWORD dst_unused:UNUSED_PAD src0_sel:WORD_1
	v_cvt_f32_f16_e32 v60, v44
	v_cvt_f32_f16_sdwa v61, v44 dst_sel:DWORD dst_unused:UNUSED_PAD src0_sel:WORD_1
	v_cvt_f32_f16_e32 v44, v45
	v_cvt_f32_f16_sdwa v45, v45 dst_sel:DWORD dst_unused:UNUSED_PAD src0_sel:WORD_1
	v_cvt_f32_f16_e32 v62, v46
	v_cvt_f32_f16_sdwa v63, v46 dst_sel:DWORD dst_unused:UNUSED_PAD src0_sel:WORD_1
	v_cvt_f32_f16_e32 v46, v47
	v_cvt_f32_f16_sdwa v47, v47 dst_sel:DWORD dst_unused:UNUSED_PAD src0_sel:WORD_1
	v_cvt_f32_f16_e32 v64, v48
	v_cvt_f32_f16_sdwa v65, v48 dst_sel:DWORD dst_unused:UNUSED_PAD src0_sel:WORD_1
	v_cvt_f32_f16_e32 v48, v49
	v_cvt_f32_f16_sdwa v49, v49 dst_sel:DWORD dst_unused:UNUSED_PAD src0_sel:WORD_1
	v_cvt_f32_f16_e32 v66, v50
	v_cvt_f32_f16_sdwa v67, v50 dst_sel:DWORD dst_unused:UNUSED_PAD src0_sel:WORD_1
	v_cvt_f32_f16_e32 v50, v51
	v_cvt_f32_f16_sdwa v51, v51 dst_sel:DWORD dst_unused:UNUSED_PAD src0_sel:WORD_1
	v_cvt_f32_f16_e32 v68, v52
	v_cvt_f32_f16_sdwa v69, v52 dst_sel:DWORD dst_unused:UNUSED_PAD src0_sel:WORD_1
	v_cvt_f32_f16_e32 v52, v53
	v_cvt_f32_f16_sdwa v53, v53 dst_sel:DWORD dst_unused:UNUSED_PAD src0_sel:WORD_1
	v_cvt_f32_f16_e32 v70, v54
	v_cvt_f32_f16_sdwa v71, v54 dst_sel:DWORD dst_unused:UNUSED_PAD src0_sel:WORD_1
	v_cvt_f32_f16_e32 v54, v55
	v_cvt_f32_f16_sdwa v55, v55 dst_sel:DWORD dst_unused:UNUSED_PAD src0_sel:WORD_1
	v_cvt_f32_f16_e32 v72, v56
	v_cvt_f32_f16_sdwa v73, v56 dst_sel:DWORD dst_unused:UNUSED_PAD src0_sel:WORD_1
	v_cvt_f32_f16_e32 v56, v57
	v_cvt_f32_f16_sdwa v57, v57 dst_sel:DWORD dst_unused:UNUSED_PAD src0_sel:WORD_1
	v_pk_fma_f32 v[40:41], v[136:137], v[2:3], v[40:41] op_sel_hi:[1,0,1]
	v_pk_fma_f32 v[58:59], v[134:135], v[2:3], v[58:59] op_sel_hi:[1,0,1]
	v_pk_fma_f32 v[44:45], v[140:141], v[2:3], v[44:45] op_sel_hi:[1,0,1]
	v_pk_fma_f32 v[60:61], v[138:139], v[2:3], v[60:61] op_sel_hi:[1,0,1]
	v_pk_fma_f32 v[46:47], v[144:145], v[2:3], v[46:47] op_sel_hi:[1,0,1]
	v_pk_fma_f32 v[62:63], v[142:143], v[2:3], v[62:63] op_sel_hi:[1,0,1]
	v_pk_fma_f32 v[48:49], v[148:149], v[2:3], v[48:49] op_sel_hi:[1,0,1]
	v_pk_fma_f32 v[64:65], v[146:147], v[2:3], v[64:65] op_sel_hi:[1,0,1]
	v_pk_fma_f32 v[50:51], v[152:153], v[2:3], v[50:51] op_sel_hi:[1,0,1]
	v_pk_fma_f32 v[66:67], v[150:151], v[2:3], v[66:67] op_sel_hi:[1,0,1]
	v_pk_fma_f32 v[52:53], v[156:157], v[2:3], v[52:53] op_sel_hi:[1,0,1]
	v_pk_fma_f32 v[68:69], v[154:155], v[2:3], v[68:69] op_sel_hi:[1,0,1]
	v_pk_fma_f32 v[54:55], v[160:161], v[2:3], v[54:55] op_sel_hi:[1,0,1]
	v_pk_fma_f32 v[70:71], v[158:159], v[2:3], v[70:71] op_sel_hi:[1,0,1]
	v_pk_fma_f32 v[56:57], v[164:165], v[2:3], v[56:57] op_sel_hi:[1,0,1]
	v_pk_fma_f32 v[72:73], v[162:163], v[2:3], v[72:73] op_sel_hi:[1,0,1]
	v_cvt_pk_f16_f32 v41, v40, v41
	v_cvt_pk_f16_f32 v40, v58, v59
	v_cvt_pk_f16_f32 v45, v44, v45
	v_cvt_pk_f16_f32 v44, v60, v61
	v_cvt_pk_f16_f32 v47, v46, v47
	v_cvt_pk_f16_f32 v46, v62, v63
	v_cvt_pk_f16_f32 v49, v48, v49
	v_cvt_pk_f16_f32 v48, v64, v65
	v_cvt_pk_f16_f32 v51, v50, v51
	v_cvt_pk_f16_f32 v50, v66, v67
	v_cvt_pk_f16_f32 v53, v52, v53
	v_cvt_pk_f16_f32 v52, v68, v69
	v_cvt_pk_f16_f32 v55, v54, v55
	v_cvt_pk_f16_f32 v54, v70, v71
	v_cvt_pk_f16_f32 v57, v56, v57
	v_cvt_pk_f16_f32 v56, v72, v73
	global_store_dwordx2 v[38:39], v[40:41], off
	global_store_dwordx2 v[38:39], v[44:45], off offset:32
	global_store_dwordx2 v[38:39], v[46:47], off offset:64
	global_store_dwordx2 v[38:39], v[48:49], off offset:96
	global_store_dwordx2 v[38:39], v[50:51], off offset:128
	global_store_dwordx2 v[38:39], v[52:53], off offset:160
	global_store_dwordx2 v[38:39], v[54:55], off offset:192
	global_store_dwordx2 v[38:39], v[56:57], off offset:224
	v_mov_b32 v5, v172
	s_waitcnt lgkmcnt(0)
	v_add_f32_e32 v39, v74, v75
	v_lshrrev_b32_e32 v2, 2, v5
	v_and_or_b32 v42, v2, 3, s28
	v_and_or_b32 v38, v5, 3, s1
	v_cmp_lt_f32_e32 vcc, 0, v39
	s_and_saveexec_b64 s[6:7], vcc
	s_cbranch_execz .LBB0_575
	v_mov_b32_e32 v2, v255
	v_cvt_f32_f16_e32 v2, v2
	v_mul_f32_e32 v2, 0xbfb8aa3b, v2
	v_exp_f32_e32 v2, v2
	s_nop 0
	v_add_f32_e32 v2, 1.0, v2
	v_div_scale_f32 v4, s[8:9], v2, v2, 1.0
	v_rcp_f32_e32 v40, v4
	v_div_scale_f32 v41, vcc, 1.0, v2, 1.0
	v_fma_f32 v44, -v4, v40, 1.0
	v_fmac_f32_e32 v40, v44, v40
	v_mul_f32_e32 v44, v41, v40
	v_fma_f32 v45, -v4, v44, v41
	v_fmac_f32_e32 v44, v45, v40
	v_fma_f32 v4, -v4, v44, v41
	v_div_fmas_f32 v4, v4, v40, v44
	v_div_fixup_f32 v2, v4, v2, 1.0
	v_mul_f32_e32 v2, 0x42800000, v2
	v_div_scale_f32 v4, s[8:9], v39, v39, v2
	v_rcp_f32_e32 v40, v4
	v_div_scale_f32 v41, vcc, v2, v39, v2
	v_fma_f32 v44, -v4, v40, 1.0
	v_fmac_f32_e32 v40, v44, v40
	v_mul_f32_e32 v44, v41, v40
	v_fma_f32 v45, -v4, v44, v41
	v_fmac_f32_e32 v44, v45, v40
	v_fma_f32 v4, -v4, v44, v41
	v_div_fmas_f32 v4, v4, v40, v44
	v_div_fixup_f32 v4, v4, v39, v2
	s_branch .LBB0_575

; __device__ __forceinline__ void attn_fast(const Ptrs& P, LAS unsigned char* lds, int G, int bid) {
;     ...
;                 const size_t row = (size_t)b * SEQ + 64 * qb + 8 * w + 4 * ct + (fr_ >> 2);
;                 float sv = 0.f; half4 yv[2][8];
; #pragma unroll
;                 for (int g2 = 0; g2 < 2; ++g2)
; #pragma unroll
;                     for (int dt = 0; dt < 8; ++dt) yv[g2][dt] = *(const half4*)(Y + row * 1024 + (4 * g2 + hh_) * 128 + 16 * dt + 4 * fq_);
; #pragma unroll
;                 for (int g2 = 0; g2 < 2; ++g2)
; #pragma unroll
;                     for (int dt = 0; dt < 8; ++dt) { const half4 h = yv[g2][dt]; const float a0 = (float)h[0], a1 = (float)h[1], a2 = (float)h[2], a3 = (float)h[3]; sv += (a0 * a0 + a1 * a1) + (a2 * a2 + a3 * a3); }
;                 sv += __shfl_xor(sv, 1); sv += __shfl_xor(sv, 2); sv += __shfl_xor(sv, 16); sv += __shfl_xor(sv, 32);
.LBB0_628:
	v_or_b32_e32 v2, s0, v50
	v_mov_b32_e32 v15, s95
	v_or_b32_e32 v14, s37, v2
	v_lshlrev_b64 v[16:17], 11, v[14:15]
	v_lshl_add_u64 v[16:17], v[12:13], 0, v[16:17]
	global_load_dwordx4 v[4:7], v[10:11], off
	global_load_dwordx2 v[18:19], v[16:17], off
	global_load_dwordx2 v[20:21], v[16:17], off offset:32
	global_load_dwordx2 v[22:23], v[16:17], off offset:64
	global_load_dwordx2 v[24:25], v[16:17], off offset:96
	global_load_dwordx2 v[26:27], v[16:17], off offset:128
	global_load_dwordx2 v[28:29], v[16:17], off offset:160
	global_load_dwordx2 v[30:31], v[16:17], off offset:192
	global_load_dwordx2 v[32:33], v[16:17], off offset:224
	global_load_dwordx2 v[34:35], v[16:17], off offset:1024
	global_load_dwordx2 v[36:37], v[16:17], off offset:1056
	global_load_dwordx2 v[54:55], v[16:17], off offset:1088
	global_load_dwordx2 v[56:57], v[16:17], off offset:1120
	global_load_dwordx2 v[58:59], v[16:17], off offset:1152
	global_load_dwordx2 v[60:61], v[16:17], off offset:1184
	global_load_dwordx2 v[62:63], v[16:17], off offset:1216
	s_nop 0
	global_load_dwordx2 v[16:17], v[16:17], off offset:1248
	v_lshlrev_b64 v[14:15], 12, v[14:15]
	v_lshl_add_u64 v[14:15], s[24:25], 0, v[14:15]
	v_lshl_add_u64 v[64:65], v[8:9], 1, v[14:15]
	s_mov_b32 s0, 0x6564000
	v_add_co_u32_e32 v66, vcc, s0, v64
	s_mov_b32 s1, 0x800000
	s_nop 0
	v_addc_co_u32_e32 v67, vcc, 0, v65, vcc
	s_waitcnt vmcnt(15)
	v_cvt_f32_f16_sdwa v69, v18 dst_sel:DWORD dst_unused:UNUSED_PAD src0_sel:WORD_1
	v_cvt_f32_f16_sdwa v71, v19 dst_sel:DWORD dst_unused:UNUSED_PAD src0_sel:WORD_1
	s_waitcnt vmcnt(14)
	v_cvt_f32_f16_sdwa v75, v21 dst_sel:DWORD dst_unused:UNUSED_PAD src0_sel:WORD_1
	v_cvt_f32_f16_sdwa v74, v20 dst_sel:DWORD dst_unused:UNUSED_PAD src0_sel:WORD_1
	v_cvt_f32_f16_e32 v68, v18
	v_cvt_f32_f16_e32 v70, v19
	v_cvt_f32_f16_e32 v72, v20
	v_cvt_f32_f16_e32 v73, v21
	s_waitcnt vmcnt(13)
	v_cvt_f32_f16_sdwa v77, v22 dst_sel:DWORD dst_unused:UNUSED_PAD src0_sel:WORD_1
	v_cvt_f32_f16_sdwa v79, v23 dst_sel:DWORD dst_unused:UNUSED_PAD src0_sel:WORD_1
	v_cvt_f32_f16_e32 v76, v22
	v_cvt_f32_f16_e32 v78, v23
	s_waitcnt vmcnt(12)
	v_cvt_f32_f16_e32 v80, v24
	v_cvt_f32_f16_sdwa v81, v24 dst_sel:DWORD dst_unused:UNUSED_PAD src0_sel:WORD_1
	v_cvt_f32_f16_e32 v82, v25
	v_cvt_f32_f16_sdwa v83, v25 dst_sel:DWORD dst_unused:UNUSED_PAD src0_sel:WORD_1
	s_waitcnt vmcnt(11)
	v_cvt_f32_f16_sdwa v87, v27 dst_sel:DWORD dst_unused:UNUSED_PAD src0_sel:WORD_1
	v_cvt_f32_f16_sdwa v86, v26 dst_sel:DWORD dst_unused:UNUSED_PAD src0_sel:WORD_1
	s_waitcnt vmcnt(9)
	v_cvt_f32_f16_e32 v92, v30
	v_cvt_f32_f16_sdwa v93, v30 dst_sel:DWORD dst_unused:UNUSED_PAD src0_sel:WORD_1
	v_cvt_f32_f16_e32 v94, v31
	v_cvt_f32_f16_sdwa v95, v31 dst_sel:DWORD dst_unused:UNUSED_PAD src0_sel:WORD_1
	s_waitcnt vmcnt(8)
	v_cvt_f32_f16_e32 v46, v32
	v_cvt_f32_f16_sdwa v47, v32 dst_sel:DWORD dst_unused:UNUSED_PAD src0_sel:WORD_1
	v_cvt_f32_f16_e32 v48, v33
	v_cvt_f32_f16_sdwa v49, v33 dst_sel:DWORD dst_unused:UNUSED_PAD src0_sel:WORD_1
	s_waitcnt vmcnt(7)
	v_cvt_f32_f16_e32 v44, v34
	v_cvt_f32_f16_e32 v45, v35
	v_cvt_f32_f16_sdwa v43, v35 dst_sel:DWORD dst_unused:UNUSED_PAD src0_sel:WORD_1
	v_cvt_f32_f16_sdwa v42, v34 dst_sel:DWORD dst_unused:UNUSED_PAD src0_sel:WORD_1
	s_waitcnt vmcnt(5)
	v_cvt_f32_f16_e32 v34, v54
	v_cvt_f32_f16_sdwa v35, v54 dst_sel:DWORD dst_unused:UNUSED_PAD src0_sel:WORD_1
	s_waitcnt vmcnt(4)
	v_cvt_f32_f16_e32 v30, v56
	v_cvt_f32_f16_sdwa v31, v56 dst_sel:DWORD dst_unused:UNUSED_PAD src0_sel:WORD_1
	v_cvt_f32_f16_e32 v32, v57
	v_cvt_f32_f16_sdwa v33, v57 dst_sel:DWORD dst_unused:UNUSED_PAD src0_sel:WORD_1
	v_mul_f32_e32 v2, v69, v69
	v_mul_f32_e32 v54, v71, v71
	v_pk_mul_f32 v[56:57], v[74:75], v[74:75]
	v_cvt_f32_f16_e32 v84, v26
	v_cvt_f32_f16_e32 v85, v27
	v_cvt_f32_f16_e32 v88, v28
	v_cvt_f32_f16_sdwa v91, v29 dst_sel:DWORD dst_unused:UNUSED_PAD src0_sel:WORD_1
	v_cvt_f32_f16_sdwa v90, v28 dst_sel:DWORD dst_unused:UNUSED_PAD src0_sel:WORD_1
	v_cvt_f32_f16_e32 v40, v36
	v_cvt_f32_f16_e32 v41, v37
	v_cvt_f32_f16_sdwa v39, v37 dst_sel:DWORD dst_unused:UNUSED_PAD src0_sel:WORD_1
	v_cvt_f32_f16_sdwa v38, v36 dst_sel:DWORD dst_unused:UNUSED_PAD src0_sel:WORD_1
	v_cvt_f32_f16_e32 v36, v55
	v_cvt_f32_f16_sdwa v37, v55 dst_sel:DWORD dst_unused:UNUSED_PAD src0_sel:WORD_1
	s_waitcnt vmcnt(3)
	v_cvt_f32_f16_e32 v28, v58
	v_cvt_f32_f16_sdwa v26, v58 dst_sel:DWORD dst_unused:UNUSED_PAD src0_sel:WORD_1
	s_waitcnt vmcnt(2)
	v_cvt_f32_f16_e32 v24, v60
	v_cvt_f32_f16_sdwa v22, v60 dst_sel:DWORD dst_unused:UNUSED_PAD src0_sel:WORD_1
	v_mul_f32_e32 v58, v77, v77
	v_mul_f32_e32 v60, v79, v79
	v_pk_fma_f32 v[134:135], v[68:69], v[68:69], v[2:3] op_sel_hi:[1,1,0]
	v_pk_fma_f32 v[54:55], v[70:71], v[70:71], v[54:55] op_sel_hi:[1,1,0]
	v_pk_fma_f32 v[56:57], v[72:73], v[72:73], v[56:57]
	v_cvt_f32_f16_e32 v89, v29
	v_cvt_f32_f16_e32 v29, v59
	v_cvt_f32_f16_sdwa v27, v59 dst_sel:DWORD dst_unused:UNUSED_PAD src0_sel:WORD_1
	v_cvt_f32_f16_e32 v25, v61
	v_cvt_f32_f16_sdwa v23, v61 dst_sel:DWORD dst_unused:UNUSED_PAD src0_sel:WORD_1
	s_waitcnt vmcnt(1)
; __device__ __forceinline__ unsigned pk_bf2(float lo, float hi) { unsigned r; asm("v_cvt_pk_bf16_f32 %0, %1, %2" : "=v"(r) : "v"(lo), "v"(hi)); return r; }
; __device__ __forceinline__ void attn_fast(const Ptrs& P, LAS unsigned char* lds, int G, int bid) {
;     ...
;                 sv += __shfl_xor(sv, 1); sv += __shfl_xor(sv, 2); sv += __shfl_xor(sv, 16); sv += __shfl_xor(sv, 32);
;                 const float rstd = rsqrtf(sv * (1.f / 1024.f) + 4096.f * EPS);
; #pragma unroll
;                 for (int g2 = 0; g2 < 2; ++g2)
; #pragma unroll
;                     for (int dt = 0; dt < 8; ++dt) { const int ch = (4 * g2 + hh_) * 128 + 16 * dt + 4 * fq_; const half4 h = yv[g2][dt];
;                         const f32x4 v = {(float)h[0], (float)h[1], (float)h[2], (float)h[3]}; const f32x4 gv = *(const f32x4*)(gw + ch); const f32x4 ov = v * rstd * gv;
;                         u32x2 wv; wv.x = pg8::pk_bf2(ov[0], ov[1]); wv.y = pg8::pk_bf2(ov[2], ov[3]);
;                         *(u32x2*)(MIX + row * DM + 1024 + ch) = wv; }
	v_cvt_f32_f16_e32 v18, v62
	v_cvt_f32_f16_sdwa v19, v62 dst_sel:DWORD dst_unused:UNUSED_PAD src0_sel:WORD_1
	v_cvt_f32_f16_e32 v20, v63
	v_cvt_f32_f16_sdwa v21, v63 dst_sel:DWORD dst_unused:UNUSED_PAD src0_sel:WORD_1
	v_pk_mul_f32 v[62:63], v[80:81], v[80:81]
	v_pk_mul_f32 v[96:97], v[82:83], v[82:83]
	v_pk_fma_f32 v[58:59], v[76:77], v[76:77], v[58:59] op_sel_hi:[1,1,0]
	v_pk_fma_f32 v[60:61], v[78:79], v[78:79], v[60:61] op_sel_hi:[1,1,0]
	v_pk_add_f32 v[56:57], v[56:57], v[56:57] op_sel:[0,1] op_sel_hi:[1,0]
	v_pk_add_f32 v[54:55], v[134:135], v[54:55]
	v_mov_b32_e32 v59, v96
	v_mov_b32_e32 v61, v97
	v_mov_b32_e32 v55, v62
	v_mov_b32_e32 v57, v63
	v_pk_mul_f32 v[98:99], v[86:87], v[86:87]
	v_pk_add_f32 v[58:59], v[58:59], v[60:61]
	v_pk_add_f32 v[54:55], v[54:55], v[56:57]
	v_pk_mul_f32 v[100:101], v[90:91], v[90:91]
	v_pk_fma_f32 v[98:99], v[84:85], v[84:85], v[98:99]
	v_pk_add_f32 v[54:55], v[54:55], v[58:59]
	v_mul_f32_e32 v102, v93, v93
	v_mul_f32_e32 v104, v95, v95
	v_pk_fma_f32 v[100:101], v[88:89], v[88:89], v[100:101]
	v_pk_add_f32 v[96:97], v[98:99], v[98:99] op_sel:[0,1] op_sel_hi:[1,0]
	v_pk_add_f32 v[54:55], v[54:55], v[54:55] op_sel:[0,1] op_sel_hi:[1,0]
	v_pk_mul_f32 v[106:107], v[46:47], v[46:47]
	v_pk_mul_f32 v[108:109], v[48:49], v[48:49]
	v_pk_fma_f32 v[102:103], v[92:93], v[92:93], v[102:103] op_sel_hi:[1,1,0]
	v_pk_fma_f32 v[104:105], v[94:95], v[94:95], v[104:105] op_sel_hi:[1,1,0]
	v_pk_add_f32 v[98:99], v[100:101], v[100:101] op_sel:[0,1] op_sel_hi:[1,0]
	v_pk_add_f32 v[54:55], v[54:55], v[96:97]
	v_mov_b32_e32 v103, v108
	v_mov_b32_e32 v105, v109
	v_mov_b32_e32 v99, v107
	v_mov_b32_e32 v55, v106
	v_pk_mul_f32 v[110:111], v[42:43], v[42:43]
	v_pk_add_f32 v[60:61], v[102:103], v[104:105]
	v_pk_add_f32 v[54:55], v[54:55], v[98:99]
	v_pk_mul_f32 v[112:113], v[38:39], v[38:39]
	v_pk_fma_f32 v[110:111], v[44:45], v[44:45], v[110:111]
	v_pk_add_f32 v[54:55], v[54:55], v[60:61]
	v_mul_f32_e32 v114, v35, v35
	v_mul_f32_e32 v116, v37, v37
	v_pk_fma_f32 v[112:113], v[40:41], v[40:41], v[112:113]
	v_pk_add_f32 v[100:101], v[110:111], v[110:111] op_sel:[0,1] op_sel_hi:[1,0]
	v_pk_add_f32 v[54:55], v[54:55], v[54:55] op_sel:[0,1] op_sel_hi:[1,0]
	v_pk_mul_f32 v[118:119], v[30:31], v[30:31]
	v_pk_mul_f32 v[120:121], v[32:33], v[32:33]
	v_pk_fma_f32 v[114:115], v[34:35], v[34:35], v[114:115] op_sel_hi:[1,1,0]
	v_pk_fma_f32 v[116:117], v[36:37], v[36:37], v[116:117] op_sel_hi:[1,1,0]
	v_pk_add_f32 v[108:109], v[112:113], v[112:113] op_sel:[0,1] op_sel_hi:[1,0]
	v_pk_add_f32 v[54:55], v[54:55], v[100:101]
	s_waitcnt vmcnt(0)
	v_cvt_f32_f16_e32 v14, v16
	v_cvt_f32_f16_sdwa v15, v16 dst_sel:DWORD dst_unused:UNUSED_PAD src0_sel:WORD_1
	v_cvt_f32_f16_e32 v16, v17
	v_cvt_f32_f16_sdwa v17, v17 dst_sel:DWORD dst_unused:UNUSED_PAD src0_sel:WORD_1
	v_mov_b32_e32 v115, v120
	v_mov_b32_e32 v117, v121
	v_mov_b32_e32 v109, v119
	v_mov_b32_e32 v55, v118
	v_pk_mul_f32 v[122:123], v[26:27], v[26:27]
	v_pk_add_f32 v[62:63], v[114:115], v[116:117]
	v_pk_add_f32 v[54:55], v[54:55], v[108:109]
	v_pk_mul_f32 v[124:125], v[22:23], v[22:23]
	v_pk_fma_f32 v[122:123], v[28:29], v[28:29], v[122:123]
	v_pk_add_f32 v[54:55], v[54:55], v[62:63]
	v_mul_f32_e32 v126, v19, v19
	v_mul_f32_e32 v128, v21, v21
	v_pk_fma_f32 v[124:125], v[24:25], v[24:25], v[124:125]
	v_pk_add_f32 v[110:111], v[122:123], v[122:123] op_sel:[0,1] op_sel_hi:[1,0]
	v_pk_add_f32 v[54:55], v[54:55], v[54:55] op_sel:[0,1] op_sel_hi:[1,0]
	v_pk_mul_f32 v[130:131], v[14:15], v[14:15]
	v_pk_mul_f32 v[132:133], v[16:17], v[16:17]
	v_pk_fma_f32 v[126:127], v[18:19], v[18:19], v[126:127] op_sel_hi:[1,1,0]
	v_pk_fma_f32 v[128:129], v[20:21], v[20:21], v[128:129] op_sel_hi:[1,1,0]
	v_pk_add_f32 v[112:113], v[124:125], v[124:125] op_sel:[0,1] op_sel_hi:[1,0]
	v_pk_add_f32 v[54:55], v[54:55], v[110:111]
	v_mov_b32_e32 v127, v132
	v_mov_b32_e32 v129, v133
	v_mov_b32_e32 v113, v131
	v_mov_b32_e32 v55, v130
	v_pk_add_f32 v[102:103], v[126:127], v[128:129]
	v_pk_add_f32 v[54:55], v[54:55], v[112:113]
	s_nop 0
	v_pk_add_f32 v[54:55], v[54:55], v[102:103]
	s_nop 0
	v_add_f32_e32 v2, v54, v55
	ds_bpermute_b32 v53, v51, v2
	s_waitcnt lgkmcnt(0)
	v_add_f32_e32 v2, v2, v53
	ds_bpermute_b32 v53, v52, v2
	s_waitcnt lgkmcnt(0)
	v_add_f32_e32 v2, v2, v53
	ds_bpermute_b32 v53, v167, v2
	s_waitcnt lgkmcnt(0)
	v_add_f32_e32 v2, v2, v53
	ds_bpermute_b32 v53, v207, v2
	s_waitcnt lgkmcnt(0)
	v_add_f32_e32 v2, v2, v53
	v_fmamk_f32 v2, v2, 0x3a800000, v200
	v_mul_f32_e32 v53, 0x4b800000, v2
	v_cmp_gt_f32_e32 vcc, s1, v2
	s_mov_b64 s[0:1], 0x6564800
	s_nop 0
	v_cndmask_b32_e32 v2, v2, v53, vcc
	v_rsq_f32_e32 v2, v2
	s_nop 0
	v_mul_f32_e32 v53, 0x45800000, v2
	v_cndmask_b32_e32 v2, v2, v53, vcc
	v_pk_mul_f32 v[54:55], v[68:69], v[2:3] op_sel_hi:[1,0]
	v_pk_mul_f32 v[56:57], v[70:71], v[2:3] op_sel_hi:[1,0]
	v_pk_mul_f32 v[4:5], v[4:5], v[54:55]
	v_pk_mul_f32 v[6:7], v[6:7], v[56:57]
	v_cvt_pk_bf16_f32 v4, v4, v5
	s_and_b64 vcc, exec, s[6:7]
	v_cvt_pk_bf16_f32 v5, v6, v7
	global_load_dwordx4 v[54:57], v[10:11], off offset:64
	global_store_dwordx2 v[66:67], v[4:5], off offset:2048
	v_mov_b32_e32 v6, v72
	v_mov_b32_e32 v7, v74
	v_mov_b32_e32 v74, v73
	v_pk_mul_f32 v[6:7], v[6:7], v[2:3] op_sel_hi:[1,0]
	v_lshl_add_u64 v[4:5], v[64:65], 0, s[0:1]
	v_pk_mul_f32 v[58:59], v[74:75], v[2:3] op_sel_hi:[1,0]
	s_mov_b32 s0, 4
	s_mov_b64 s[6:7], 0
	s_waitcnt vmcnt(1)
	v_pk_mul_f32 v[6:7], v[54:55], v[6:7]
	v_pk_mul_f32 v[56:57], v[56:57], v[58:59]
	v_cvt_pk_bf16_f32 v6, v6, v7
	v_pk_mul_f32 v[58:59], v[78:79], v[2:3] op_sel_hi:[1,0]
	v_cvt_pk_bf16_f32 v7, v56, v57
	global_load_dwordx4 v[54:57], v[10:11], off offset:128
	global_store_dwordx2 v[4:5], v[6:7], off offset:32
	v_pk_mul_f32 v[6:7], v[76:77], v[2:3] op_sel_hi:[1,0]
	s_waitcnt vmcnt(1)
; __device__ __forceinline__ unsigned pk_bf2(float lo, float hi) { unsigned r; asm("v_cvt_pk_bf16_f32 %0, %1, %2" : "=v"(r) : "v"(lo), "v"(hi)); return r; }
; __device__ __forceinline__ void attn_fast(const Ptrs& P, LAS unsigned char* lds, int G, int bid) {
;     ...
; #pragma unroll
;                 for (int g2 = 0; g2 < 2; ++g2)
; #pragma unroll
;                     for (int dt = 0; dt < 8; ++dt) { const int ch = (4 * g2 + hh_) * 128 + 16 * dt + 4 * fq_; const half4 h = yv[g2][dt];
;                         const f32x4 v = {(float)h[0], (float)h[1], (float)h[2], (float)h[3]}; const f32x4 gv = *(const f32x4*)(gw + ch); const f32x4 ov = v * rstd * gv;
;                         u32x2 wv; wv.x = pg8::pk_bf2(ov[0], ov[1]); wv.y = pg8::pk_bf2(ov[2], ov[3]);
;                         *(u32x2*)(MIX + row * DM + 1024 + ch) = wv; }
	v_pk_mul_f32 v[56:57], v[56:57], v[58:59]
	v_pk_mul_f32 v[6:7], v[54:55], v[6:7]
	v_pk_mul_f32 v[58:59], v[82:83], v[2:3] op_sel_hi:[1,0]
	v_cvt_pk_bf16_f32 v6, v6, v7
	v_cvt_pk_bf16_f32 v7, v56, v57
	global_load_dwordx4 v[54:57], v[10:11], off offset:192
	global_store_dwordx2 v[4:5], v[6:7], off offset:64
	v_pk_mul_f32 v[6:7], v[80:81], v[2:3] op_sel_hi:[1,0]
	s_waitcnt vmcnt(1)
	v_pk_mul_f32 v[56:57], v[56:57], v[58:59]
	v_pk_mul_f32 v[6:7], v[54:55], v[6:7]
	s_nop 0
	v_cvt_pk_bf16_f32 v6, v6, v7
	v_cvt_pk_bf16_f32 v7, v56, v57
	global_load_dwordx4 v[54:57], v[10:11], off offset:256
	global_store_dwordx2 v[4:5], v[6:7], off offset:96
	v_mov_b32_e32 v6, v84
	v_mov_b32_e32 v7, v86
	v_mov_b32_e32 v86, v85
	v_pk_mul_f32 v[6:7], v[6:7], v[2:3] op_sel_hi:[1,0]
	v_pk_mul_f32 v[58:59], v[86:87], v[2:3] op_sel_hi:[1,0]
	s_waitcnt vmcnt(1)
	v_pk_mul_f32 v[6:7], v[54:55], v[6:7]
	v_pk_mul_f32 v[56:57], v[56:57], v[58:59]
	v_cvt_pk_bf16_f32 v6, v6, v7
	s_nop 0
	v_cvt_pk_bf16_f32 v7, v56, v57
	global_load_dwordx4 v[54:57], v[10:11], off offset:320
	global_store_dwordx2 v[4:5], v[6:7], off offset:128
	v_mov_b32_e32 v6, v88
	v_mov_b32_e32 v7, v90
	v_mov_b32_e32 v90, v89
	v_pk_mul_f32 v[6:7], v[6:7], v[2:3] op_sel_hi:[1,0]
	v_pk_mul_f32 v[58:59], v[90:91], v[2:3] op_sel_hi:[1,0]
	s_waitcnt vmcnt(1)
	v_pk_mul_f32 v[6:7], v[6:7], v[54:55]
	v_pk_mul_f32 v[56:57], v[58:59], v[56:57]
	v_cvt_pk_bf16_f32 v6, v6, v7
	v_pk_mul_f32 v[58:59], v[94:95], v[2:3] op_sel_hi:[1,0]
	v_cvt_pk_bf16_f32 v7, v56, v57
	global_load_dwordx4 v[54:57], v[10:11], off offset:384
	global_store_dwordx2 v[4:5], v[6:7], off offset:160
	v_pk_mul_f32 v[6:7], v[92:93], v[2:3] op_sel_hi:[1,0]
	s_waitcnt vmcnt(1)
	v_pk_mul_f32 v[56:57], v[58:59], v[56:57]
	v_pk_mul_f32 v[6:7], v[6:7], v[54:55]
	s_nop 0
	v_cvt_pk_bf16_f32 v6, v6, v7
	v_cvt_pk_bf16_f32 v7, v56, v57
	global_load_dwordx4 v[54:57], v[10:11], off offset:448
	global_store_dwordx2 v[4:5], v[6:7], off offset:192
	v_pk_mul_f32 v[6:7], v[46:47], v[2:3] op_sel_hi:[1,0]
	v_pk_mul_f32 v[46:47], v[48:49], v[2:3] op_sel_hi:[1,0]
	s_waitcnt vmcnt(1)
	v_pk_mul_f32 v[6:7], v[6:7], v[54:55]
	v_pk_mul_f32 v[46:47], v[46:47], v[56:57]
	v_cvt_pk_bf16_f32 v6, v6, v7
	s_nop 0
	v_cvt_pk_bf16_f32 v7, v46, v47
	global_load_dwordx4 v[46:49], v[10:11], off offset:2048
	global_store_dwordx2 v[4:5], v[6:7], off offset:224
	v_mov_b32_e32 v6, v44
	v_mov_b32_e32 v7, v42
	v_mov_b32_e32 v42, v45
	v_pk_mul_f32 v[6:7], v[6:7], v[2:3] op_sel_hi:[1,0]
	v_pk_mul_f32 v[42:43], v[42:43], v[2:3] op_sel_hi:[1,0]
	s_waitcnt vmcnt(1)
	v_pk_mul_f32 v[6:7], v[6:7], v[46:47]
	v_pk_mul_f32 v[42:43], v[42:43], v[48:49]
	v_cvt_pk_bf16_f32 v6, v6, v7
	s_nop 0
	v_cvt_pk_bf16_f32 v7, v42, v43
	global_load_dwordx4 v[42:45], v[10:11], off offset:2112
	global_store_dwordx2 v[4:5], v[6:7], off offset:1024
	v_mov_b32_e32 v6, v40
	v_mov_b32_e32 v7, v38
	v_mov_b32_e32 v38, v41
	v_pk_mul_f32 v[6:7], v[6:7], v[2:3] op_sel_hi:[1,0]
	v_pk_mul_f32 v[38:39], v[38:39], v[2:3] op_sel_hi:[1,0]
	s_waitcnt vmcnt(1)
	v_pk_mul_f32 v[6:7], v[6:7], v[42:43]
	v_pk_mul_f32 v[38:39], v[38:39], v[44:45]
	v_cvt_pk_bf16_f32 v6, v6, v7
	s_nop 0
	v_cvt_pk_bf16_f32 v7, v38, v39
	global_load_dwordx4 v[38:41], v[10:11], off offset:2176
	global_store_dwordx2 v[4:5], v[6:7], off offset:1056
	v_pk_mul_f32 v[6:7], v[34:35], v[2:3] op_sel_hi:[1,0]
	v_pk_mul_f32 v[34:35], v[36:37], v[2:3] op_sel_hi:[1,0]
	s_waitcnt vmcnt(1)
	v_pk_mul_f32 v[6:7], v[6:7], v[38:39]
	v_pk_mul_f32 v[34:35], v[34:35], v[40:41]
	v_cvt_pk_bf16_f32 v6, v6, v7
	s_nop 0
	v_cvt_pk_bf16_f32 v7, v34, v35
	global_load_dwordx4 v[34:37], v[10:11], off offset:2240
	global_store_dwordx2 v[4:5], v[6:7], off offset:1088
	v_pk_mul_f32 v[6:7], v[30:31], v[2:3] op_sel_hi:[1,0]
	v_pk_mul_f32 v[30:31], v[32:33], v[2:3] op_sel_hi:[1,0]
	s_waitcnt vmcnt(1)
	v_pk_mul_f32 v[6:7], v[6:7], v[34:35]
	v_pk_mul_f32 v[30:31], v[30:31], v[36:37]
	v_cvt_pk_bf16_f32 v6, v6, v7
	s_nop 0
	v_cvt_pk_bf16_f32 v7, v30, v31
	global_load_dwordx4 v[30:33], v[10:11], off offset:2304
	global_store_dwordx2 v[4:5], v[6:7], off offset:1120
	v_mov_b32_e32 v6, v28
	v_mov_b32_e32 v7, v26
	v_mov_b32_e32 v26, v29
	v_pk_mul_f32 v[6:7], v[6:7], v[2:3] op_sel_hi:[1,0]
	v_pk_mul_f32 v[26:27], v[26:27], v[2:3] op_sel_hi:[1,0]
	s_waitcnt vmcnt(1)
	v_pk_mul_f32 v[6:7], v[6:7], v[30:31]
	v_pk_mul_f32 v[26:27], v[26:27], v[32:33]
	v_cvt_pk_bf16_f32 v6, v6, v7
	s_nop 0
	v_cvt_pk_bf16_f32 v7, v26, v27
	global_load_dwordx4 v[26:29], v[10:11], off offset:2368
	global_store_dwordx2 v[4:5], v[6:7], off offset:1152
	v_mov_b32_e32 v6, v24
	v_mov_b32_e32 v7, v22
	v_mov_b32_e32 v22, v25
	v_pk_mul_f32 v[6:7], v[6:7], v[2:3] op_sel_hi:[1,0]
	v_pk_mul_f32 v[22:23], v[22:23], v[2:3] op_sel_hi:[1,0]
	s_waitcnt vmcnt(1)
	v_pk_mul_f32 v[6:7], v[6:7], v[26:27]
	v_pk_mul_f32 v[22:23], v[22:23], v[28:29]
	v_cvt_pk_bf16_f32 v6, v6, v7
	s_nop 0
	v_cvt_pk_bf16_f32 v7, v22, v23
	global_load_dwordx4 v[22:25], v[10:11], off offset:2432
	global_store_dwordx2 v[4:5], v[6:7], off offset:1184
	v_pk_mul_f32 v[6:7], v[18:19], v[2:3] op_sel_hi:[1,0]
	v_pk_mul_f32 v[18:19], v[20:21], v[2:3] op_sel_hi:[1,0]
	s_waitcnt vmcnt(1)
	v_pk_mul_f32 v[6:7], v[6:7], v[22:23]
	v_pk_mul_f32 v[18:19], v[18:19], v[24:25]
	v_cvt_pk_bf16_f32 v6, v6, v7
	s_nop 0
	v_cvt_pk_bf16_f32 v7, v18, v19
	global_load_dwordx4 v[18:21], v[10:11], off offset:2496
	global_store_dwordx2 v[4:5], v[6:7], off offset:1216
	v_pk_mul_f32 v[6:7], v[14:15], v[2:3] op_sel_hi:[1,0]
	v_pk_mul_f32 v[14:15], v[16:17], v[2:3] op_sel_hi:[1,0]
	s_waitcnt vmcnt(1)
	v_pk_mul_f32 v[6:7], v[6:7], v[18:19]
	v_pk_mul_f32 v[14:15], v[14:15], v[20:21]
	v_cvt_pk_bf16_f32 v6, v6, v7
	s_nop 0
	v_cvt_pk_bf16_f32 v7, v14, v15
	global_store_dwordx2 v[4:5], v[6:7], off offset:1248
	s_cbranch_vccnz .LBB0_628
	s_load_dword s95, s[96:97], 0xc0
	v_readlane_b32 s14, v243, 11
	s_mov_b32 s0, 0
	v_readlane_b32 s12, v243, 10
	v_readlane_b32 s15, v243, 12
	s_branch .LBB0_505

; template <bool BF> __device__ __forceinline__ unsigned pk2(float lo, float hi) { return BF ? pk_bf2(lo, hi) : pk_h2(lo, hi); }
;     __device__ __forceinline__ void operator()(const f32x4 (&acc)[2][2][4][2], const Unit& u, int wr, int wc, int fr, int fq) const {
;     ...
;             for (int m = 0; m < 4; ++m) { h16* rowp = O + (size_t)(row0 + ai * HALF + m * 16) * ldc + col0;
; #pragma unroll
;                 for (int bj = 0; bj < 2; ++bj) { f32x4 v0 = acc[ai][bj][m][0], v1 = acc[ai][bj][m][1];
;                     if (ACT == 1) {
; #pragma unroll
;                         for (int j = 0; j < 4; ++j) { const float a = fmaxf(v0[j], 0.f), b = fmaxf(v1[j], 0.f); v0[j] = a * a; v1[j] = b * b; } }
;                     u32x4 w; w.x = pk2<BF>(v0[0], v0[1]); w.y = pk2<BF>(v0[2], v0[3]); w.z = pk2<BF>(v1[0], v1[1]); w.w = pk2<BF>(v1[2], v1[3]);
;                     *(u32x4*)(rowp + bj * HALF) = w; } }
.LBB0_872:
	v_lshl_add_u32 v154, s38, 8, v148
	v_ashrrev_i32_e32 v155, 31, v154
	v_max_f32_e32 v122, 0, v122
	v_lshl_or_b32 v146, s59, 8, v150
	v_lshlrev_b64 v[156:157], 14, v[154:155]
	v_mul_f32_e32 v155, v122, v122
	v_max_f32_e32 v123, 0, v123
	v_max_f32_e32 v124, 0, v124
	v_ashrrev_i32_e32 v147, 31, v146
	v_max_f32_e32 v122, 0, v127
	v_mul_f32_e32 v127, v123, v123
	v_max_f32_e32 v123, v128, v128
	v_mul_f32_e32 v128, v124, v124
	v_lshl_add_u64 v[156:157], s[8:9], 0, v[156:157]
	v_lshlrev_b64 v[158:159], 1, v[146:147]
	v_max_f32_e32 v126, 0, v126
	v_mul_f32_e32 v122, v122, v122
	v_max_f32_e32 v123, 0, v123
	v_max_f32_e32 v124, 0, v129
	v_max_f32_e32 v125, 0, v125
	v_lshl_add_u64 v[146:147], v[156:157], 0, v[158:159]
	v_mul_f32_e32 v126, v126, v126
	v_mul_f32_e32 v123, v123, v123
	v_mul_f32_e32 v124, v124, v124
	v_mul_f32_e32 v125, v125, v125
	v_cvt_pk_bf16_f32 v122, v126, v122
	v_max_f32_e32 v114, 0, v114
	v_cvt_pk_bf16_f32 v123, v123, v124
	v_cvt_pk_bf16_f32 v124, v155, v127
	v_cvt_pk_bf16_f32 v125, v128, v125
	global_store_dwordx4 v[146:147], v[122:125], off
	v_max_f32_e32 v115, 0, v115
	v_max_f32_e32 v116, 0, v116
	v_mul_f32_e32 v122, v114, v114
	v_max_f32_e32 v114, 0, v119
	v_mul_f32_e32 v119, v115, v115
	v_max_f32_e32 v115, v120, v120
	v_mul_f32_e32 v120, v116, v116
	v_max_f32_e32 v118, 0, v118
	v_mul_f32_e32 v114, v114, v114
	v_max_f32_e32 v115, 0, v115
	v_max_f32_e32 v116, 0, v121
	v_max_f32_e32 v117, 0, v117
	v_mul_f32_e32 v118, v118, v118
	v_mul_f32_e32 v115, v115, v115
	v_mul_f32_e32 v116, v116, v116
	v_mul_f32_e32 v117, v117, v117
	v_cvt_pk_bf16_f32 v114, v118, v114
	v_cvt_pk_bf16_f32 v115, v115, v116
	v_cvt_pk_bf16_f32 v116, v122, v119
	v_cvt_pk_bf16_f32 v117, v120, v117
	global_store_dwordx4 v[146:147], v[114:117], off offset:256
	s_nop 0
	v_max_f32_e32 v106, 0, v106
	v_or_b32_e32 v114, 16, v154
	v_ashrrev_i32_e32 v115, 31, v114
	v_mul_f32_e32 v116, v106, v106
	v_max_f32_e32 v107, 0, v107
	v_max_f32_e32 v108, 0, v108
	v_lshlrev_b64 v[114:115], 14, v[114:115]
	v_max_f32_e32 v106, 0, v111
	v_mul_f32_e32 v111, v107, v107
	v_max_f32_e32 v107, v112, v112
	v_mul_f32_e32 v112, v108, v108
	v_lshl_add_u64 v[114:115], s[8:9], 0, v[114:115]
	v_max_f32_e32 v110, 0, v110
	v_mul_f32_e32 v106, v106, v106
	v_max_f32_e32 v107, 0, v107
	v_max_f32_e32 v108, 0, v113
	v_max_f32_e32 v109, 0, v109
	v_lshl_add_u64 v[114:115], v[114:115], 0, v[158:159]
	v_mul_f32_e32 v110, v110, v110
	v_mul_f32_e32 v107, v107, v107
	v_mul_f32_e32 v108, v108, v108
	v_mul_f32_e32 v109, v109, v109
	v_cvt_pk_bf16_f32 v106, v110, v106
	v_max_f32_e32 v98, 0, v98
	v_cvt_pk_bf16_f32 v107, v107, v108
	v_cvt_pk_bf16_f32 v108, v116, v111
	v_cvt_pk_bf16_f32 v109, v112, v109
	global_store_dwordx4 v[114:115], v[106:109], off
	v_max_f32_e32 v99, 0, v99
	v_max_f32_e32 v100, 0, v100
	v_mul_f32_e32 v106, v98, v98
	v_max_f32_e32 v98, 0, v103
	v_mul_f32_e32 v103, v99, v99
	v_max_f32_e32 v99, v104, v104
	v_mul_f32_e32 v104, v100, v100
	v_max_f32_e32 v102, 0, v102
	v_mul_f32_e32 v98, v98, v98
	v_max_f32_e32 v99, 0, v99
	v_max_f32_e32 v100, 0, v105
	v_max_f32_e32 v101, 0, v101
	v_mul_f32_e32 v102, v102, v102
	v_mul_f32_e32 v99, v99, v99
	v_mul_f32_e32 v100, v100, v100
	v_mul_f32_e32 v101, v101, v101
	v_cvt_pk_bf16_f32 v98, v102, v98
	v_cvt_pk_bf16_f32 v99, v99, v100
	v_cvt_pk_bf16_f32 v100, v106, v103
	v_cvt_pk_bf16_f32 v101, v104, v101
	global_store_dwordx4 v[114:115], v[98:101], off offset:256
	s_nop 0
	v_max_f32_e32 v90, 0, v90
	v_or_b32_e32 v98, 32, v154
	v_ashrrev_i32_e32 v99, 31, v98
	v_mul_f32_e32 v100, v90, v90
	v_max_f32_e32 v91, 0, v91
	v_max_f32_e32 v92, 0, v92
	v_lshlrev_b64 v[98:99], 14, v[98:99]
	v_max_f32_e32 v90, 0, v95
	v_mul_f32_e32 v95, v91, v91
	v_max_f32_e32 v91, v96, v96
	v_mul_f32_e32 v96, v92, v92
	v_lshl_add_u64 v[98:99], s[8:9], 0, v[98:99]
	v_max_f32_e32 v94, 0, v94
	v_mul_f32_e32 v90, v90, v90
	v_max_f32_e32 v91, 0, v91
	v_max_f32_e32 v92, 0, v97
	v_max_f32_e32 v93, 0, v93
	v_lshl_add_u64 v[98:99], v[98:99], 0, v[158:159]
	v_mul_f32_e32 v94, v94, v94
	v_mul_f32_e32 v91, v91, v91
	v_mul_f32_e32 v92, v92, v92
	v_mul_f32_e32 v93, v93, v93
	v_cvt_pk_bf16_f32 v90, v94, v90
	v_max_f32_e32 v82, 0, v82
	v_cvt_pk_bf16_f32 v91, v91, v92
	v_cvt_pk_bf16_f32 v92, v100, v95
	v_cvt_pk_bf16_f32 v93, v96, v93
	global_store_dwordx4 v[98:99], v[90:93], off
	v_max_f32_e32 v83, 0, v83
	v_max_f32_e32 v84, 0, v84
	v_mul_f32_e32 v90, v82, v82
	v_max_f32_e32 v82, 0, v87
	v_mul_f32_e32 v87, v83, v83
	v_max_f32_e32 v83, v88, v88
	v_mul_f32_e32 v88, v84, v84
	v_max_f32_e32 v86, 0, v86
	v_mul_f32_e32 v82, v82, v82
	v_max_f32_e32 v83, 0, v83
	v_max_f32_e32 v84, 0, v89
	v_max_f32_e32 v85, 0, v85
	v_mul_f32_e32 v86, v86, v86
	v_mul_f32_e32 v83, v83, v83
	v_mul_f32_e32 v84, v84, v84
	v_mul_f32_e32 v85, v85, v85
	v_cvt_pk_bf16_f32 v82, v86, v82
	v_cvt_pk_bf16_f32 v83, v83, v84
	v_cvt_pk_bf16_f32 v84, v90, v87
	v_cvt_pk_bf16_f32 v85, v88, v85
	global_store_dwordx4 v[98:99], v[82:85], off offset:256
	s_nop 0
	v_max_f32_e32 v74, 0, v74
	v_or_b32_e32 v82, 48, v154
	v_ashrrev_i32_e32 v83, 31, v82
	v_mul_f32_e32 v84, v74, v74
	v_max_f32_e32 v75, 0, v75
	v_max_f32_e32 v76, 0, v76
	v_lshlrev_b64 v[82:83], 14, v[82:83]
	v_max_f32_e32 v74, 0, v79
	v_mul_f32_e32 v79, v75, v75
	v_max_f32_e32 v75, v80, v80
	v_mul_f32_e32 v80, v76, v76
	v_lshl_add_u64 v[82:83], s[8:9], 0, v[82:83]
	v_max_f32_e32 v78, 0, v78
	v_mul_f32_e32 v74, v74, v74
	v_max_f32_e32 v75, 0, v75
	v_max_f32_e32 v76, 0, v81
	v_max_f32_e32 v77, 0, v77
	v_lshl_add_u64 v[82:83], v[82:83], 0, v[158:159]
	v_mul_f32_e32 v78, v78, v78
	v_mul_f32_e32 v75, v75, v75
	v_mul_f32_e32 v76, v76, v76
	v_mul_f32_e32 v77, v77, v77
	v_cvt_pk_bf16_f32 v74, v78, v74
; template <bool BF> __device__ __forceinline__ unsigned pk2(float lo, float hi) { return BF ? pk_bf2(lo, hi) : pk_h2(lo, hi); }
;     __device__ __forceinline__ void operator()(const f32x4 (&acc)[2][2][4][2], const Unit& u, int wr, int wc, int fr, int fq) const {
;     ...
;             for (int m = 0; m < 4; ++m) { h16* rowp = O + (size_t)(row0 + ai * HALF + m * 16) * ldc + col0;
; #pragma unroll
;                 for (int bj = 0; bj < 2; ++bj) { f32x4 v0 = acc[ai][bj][m][0], v1 = acc[ai][bj][m][1];
;                     if (ACT == 1) {
; #pragma unroll
;                         for (int j = 0; j < 4; ++j) { const float a = fmaxf(v0[j], 0.f), b = fmaxf(v1[j], 0.f); v0[j] = a * a; v1[j] = b * b; } }
;                     u32x4 w; w.x = pk2<BF>(v0[0], v0[1]); w.y = pk2<BF>(v0[2], v0[3]); w.z = pk2<BF>(v1[0], v1[1]); w.w = pk2<BF>(v1[2], v1[3]);
;                     *(u32x4*)(rowp + bj * HALF) = w; } }
	v_max_f32_e32 v66, 0, v66
	v_max_f32_e32 v67, 0, v67
	v_max_f32_e32 v68, 0, v68
	v_cvt_pk_bf16_f32 v75, v75, v76
	v_cvt_pk_bf16_f32 v76, v84, v79
	v_cvt_pk_bf16_f32 v77, v80, v77
	global_store_dwordx4 v[82:83], v[74:77], off
	s_nop 1
	v_mul_f32_e32 v74, v66, v66
	v_max_f32_e32 v66, v71, v71
	v_mul_f32_e32 v71, v67, v67
	v_max_f32_e32 v67, v72, v72
	v_mul_f32_e32 v72, v68, v68
	v_max_f32_e32 v67, 0, v67
	v_max_f32_e32 v68, 0, v73
	v_max_f32_e32 v66, 0, v66
	v_mul_f32_e32 v67, v67, v67
	v_max_f32_e32 v69, 0, v69
	v_mul_f32_e32 v68, v68, v68
	v_max_f32_e32 v70, 0, v70
	v_mul_f32_e32 v66, v66, v66
	v_mul_f32_e32 v69, v69, v69
	v_cvt_pk_bf16_f32 v67, v67, v68
	v_cvt_pk_bf16_f32 v68, v74, v71
	v_max_f32_e32 v58, 0, v58
	v_mul_f32_e32 v70, v70, v70
	v_cvt_pk_bf16_f32 v66, v70, v66
	v_cvt_pk_bf16_f32 v69, v72, v69
	global_store_dwordx4 v[82:83], v[66:69], off offset:256
	s_nop 0
	v_max_f32_e32 v59, 0, v59
	v_mul_f32_e32 v68, v58, v58
	v_max_f32_e32 v60, 0, v60
	v_max_f32_e32 v62, 0, v62
	v_max_f32_e32 v58, 0, v63
	v_mul_f32_e32 v63, v59, v59
	v_max_f32_e32 v59, v64, v64
	v_mul_f32_e32 v64, v60, v60
	v_mul_f32_e32 v62, v62, v62
	v_mul_f32_e32 v58, v58, v58
	v_max_f32_e32 v59, 0, v59
	v_max_f32_e32 v60, 0, v65
	v_mul_f32_e32 v59, v59, v59
	v_max_f32_e32 v61, 0, v61
	v_mul_f32_e32 v60, v60, v60
	v_cvt_pk_bf16_f32 v58, v62, v58
	v_add_co_u32_e32 v62, vcc, s55, v146
	v_mul_f32_e32 v61, v61, v61
	v_cvt_pk_bf16_f32 v59, v59, v60
	v_cvt_pk_bf16_f32 v60, v68, v63
	v_addc_co_u32_e32 v63, vcc, 0, v147, vcc
	v_max_f32_e32 v50, 0, v50
	v_max_f32_e32 v51, 0, v51
	v_max_f32_e32 v52, 0, v52
	v_cvt_pk_bf16_f32 v61, v64, v61
	global_store_dwordx4 v[62:63], v[58:61], off
	s_nop 1
	v_mul_f32_e32 v58, v50, v50
	v_max_f32_e32 v50, v55, v55
	v_mul_f32_e32 v55, v51, v51
	v_max_f32_e32 v51, v56, v56
	v_mul_f32_e32 v56, v52, v52
	v_max_f32_e32 v51, 0, v51
	v_max_f32_e32 v52, 0, v57
	v_max_f32_e32 v50, 0, v50
	v_mul_f32_e32 v51, v51, v51
	v_max_f32_e32 v53, 0, v53
	v_mul_f32_e32 v52, v52, v52
	v_lshl_add_u64 v[66:67], v[146:147], 0, s[16:17]
	v_max_f32_e32 v54, 0, v54
	v_mul_f32_e32 v50, v50, v50
	v_mul_f32_e32 v53, v53, v53
	v_cvt_pk_bf16_f32 v51, v51, v52
	v_cvt_pk_bf16_f32 v52, v58, v55
	v_max_f32_e32 v42, 0, v42
	v_mul_f32_e32 v54, v54, v54
	v_cvt_pk_bf16_f32 v50, v54, v50
	v_cvt_pk_bf16_f32 v53, v56, v53
	global_store_dwordx4 v[66:67], v[50:53], off offset:256
	s_nop 0
	v_max_f32_e32 v43, 0, v43
	v_mul_f32_e32 v52, v42, v42
	v_max_f32_e32 v44, 0, v44
	v_max_f32_e32 v46, 0, v46
	v_max_f32_e32 v42, 0, v47
	v_mul_f32_e32 v47, v43, v43
	v_max_f32_e32 v43, v48, v48
	v_mul_f32_e32 v48, v44, v44
	v_mul_f32_e32 v46, v46, v46
	v_mul_f32_e32 v42, v42, v42
	v_max_f32_e32 v43, 0, v43
	v_max_f32_e32 v44, 0, v49
	v_mul_f32_e32 v43, v43, v43
	v_max_f32_e32 v45, 0, v45
	v_mul_f32_e32 v44, v44, v44
	v_cvt_pk_bf16_f32 v42, v46, v42
	v_add_co_u32_e32 v46, vcc, s56, v146
	v_mul_f32_e32 v45, v45, v45
	v_cvt_pk_bf16_f32 v43, v43, v44
	v_cvt_pk_bf16_f32 v44, v52, v47
	v_addc_co_u32_e32 v47, vcc, 0, v147, vcc
	v_max_f32_e32 v34, 0, v34
	v_max_f32_e32 v35, 0, v35
	v_max_f32_e32 v36, 0, v36
	v_cvt_pk_bf16_f32 v45, v48, v45
	global_store_dwordx4 v[46:47], v[42:45], off
	s_nop 1
	v_mul_f32_e32 v42, v34, v34
	v_max_f32_e32 v34, v39, v39
	v_mul_f32_e32 v39, v35, v35
	v_max_f32_e32 v35, v40, v40
	v_mul_f32_e32 v40, v36, v36
	v_max_f32_e32 v35, 0, v35
	v_max_f32_e32 v36, 0, v41
	v_max_f32_e32 v34, 0, v34
	v_mul_f32_e32 v35, v35, v35
	v_max_f32_e32 v37, 0, v37
	v_mul_f32_e32 v36, v36, v36
	v_lshl_add_u64 v[50:51], v[146:147], 0, s[18:19]
	v_max_f32_e32 v38, 0, v38
	v_mul_f32_e32 v34, v34, v34
	v_mul_f32_e32 v37, v37, v37
	v_cvt_pk_bf16_f32 v35, v35, v36
	v_cvt_pk_bf16_f32 v36, v42, v39
	v_max_f32_e32 v26, 0, v26
	v_mul_f32_e32 v38, v38, v38
	v_cvt_pk_bf16_f32 v34, v38, v34
	v_cvt_pk_bf16_f32 v37, v40, v37
	global_store_dwordx4 v[50:51], v[34:37], off offset:256
	s_nop 0
	v_max_f32_e32 v27, 0, v27
	v_mul_f32_e32 v36, v26, v26
	v_max_f32_e32 v28, 0, v28
	v_max_f32_e32 v30, 0, v30
	v_max_f32_e32 v26, 0, v31
	v_mul_f32_e32 v31, v27, v27
	v_max_f32_e32 v27, v32, v32
	v_mul_f32_e32 v32, v28, v28
	v_mul_f32_e32 v30, v30, v30
	v_mul_f32_e32 v26, v26, v26
	v_max_f32_e32 v27, 0, v27
	v_max_f32_e32 v28, 0, v33
	v_mul_f32_e32 v27, v27, v27
	v_max_f32_e32 v29, 0, v29
	v_mul_f32_e32 v28, v28, v28
	v_cvt_pk_bf16_f32 v26, v30, v26
	v_add_co_u32_e32 v30, vcc, s57, v146
	v_mul_f32_e32 v29, v29, v29
	v_cvt_pk_bf16_f32 v27, v27, v28
	v_cvt_pk_bf16_f32 v28, v36, v31
	v_addc_co_u32_e32 v31, vcc, 0, v147, vcc
	v_max_f32_e32 v18, 0, v18
	v_max_f32_e32 v19, 0, v19
	v_max_f32_e32 v20, 0, v20
	v_cvt_pk_bf16_f32 v29, v32, v29
	global_store_dwordx4 v[30:31], v[26:29], off
	s_nop 1
	v_mul_f32_e32 v26, v18, v18
	v_max_f32_e32 v18, v23, v23
	v_mul_f32_e32 v23, v19, v19
	v_max_f32_e32 v19, v24, v24
	v_mul_f32_e32 v24, v20, v20
	v_max_f32_e32 v19, 0, v19
	v_max_f32_e32 v20, 0, v25
	v_max_f32_e32 v18, 0, v18
	v_mul_f32_e32 v19, v19, v19
	v_max_f32_e32 v21, 0, v21
	v_mul_f32_e32 v20, v20, v20
	v_lshl_add_u64 v[34:35], v[146:147], 0, s[20:21]
	v_max_f32_e32 v22, 0, v22
	v_mul_f32_e32 v18, v18, v18
	v_mul_f32_e32 v21, v21, v21
	v_cvt_pk_bf16_f32 v19, v19, v20
	v_cvt_pk_bf16_f32 v20, v26, v23
	v_max_f32_e32 v10, 0, v10
	v_mul_f32_e32 v22, v22, v22
	v_cvt_pk_bf16_f32 v18, v22, v18
	v_cvt_pk_bf16_f32 v21, v24, v21
	global_store_dwordx4 v[34:35], v[18:21], off offset:256
	s_nop 0
	v_max_f32_e32 v11, 0, v11
	v_mul_f32_e32 v20, v10, v10
	v_max_f32_e32 v12, 0, v12
	v_max_f32_e32 v14, 0, v14
	v_max_f32_e32 v10, 0, v15
	v_mul_f32_e32 v15, v11, v11
	v_max_f32_e32 v11, v16, v16
	v_mul_f32_e32 v16, v12, v12
	v_mul_f32_e32 v14, v14, v14
	v_mul_f32_e32 v10, v10, v10
	v_max_f32_e32 v11, 0, v11
	v_max_f32_e32 v12, 0, v17
	v_mul_f32_e32 v11, v11, v11
	v_max_f32_e32 v13, 0, v13
	v_mul_f32_e32 v12, v12, v12
	v_cvt_pk_bf16_f32 v10, v14, v10
	v_add_co_u32_e32 v14, vcc, s58, v146
	v_mul_f32_e32 v13, v13, v13
	v_cvt_pk_bf16_f32 v11, v11, v12
	v_cvt_pk_bf16_f32 v12, v20, v15
	v_addc_co_u32_e32 v15, vcc, 0, v147, vcc
	v_max_f32_e32 v2, 0, v2
	v_max_f32_e32 v3, 0, v3
	v_max_f32_e32 v4, 0, v4
	v_cvt_pk_bf16_f32 v13, v16, v13
	global_store_dwordx4 v[14:15], v[10:13], off
	s_nop 1
	v_mul_f32_e32 v10, v2, v2
	v_max_f32_e32 v2, v7, v7
	v_mul_f32_e32 v7, v3, v3
	v_max_f32_e32 v3, v8, v8
	v_mul_f32_e32 v8, v4, v4
	v_max_f32_e32 v2, 0, v2
	v_max_f32_e32 v3, 0, v3
	v_max_f32_e32 v4, 0, v9
	v_max_f32_e32 v5, 0, v5
	v_lshl_add_u64 v[18:19], v[146:147], 0, s[22:23]
	v_max_f32_e32 v6, 0, v6
	v_mul_f32_e32 v2, v2, v2
	v_mul_f32_e32 v3, v3, v3
	v_mul_f32_e32 v4, v4, v4
	v_mul_f32_e32 v5, v5, v5
	s_andn2_b64 vcc, exec, s[4:5]
	s_mov_b64 s[4:5], -1
	v_mul_f32_e32 v6, v6, v6
	v_cvt_pk_bf16_f32 v2, v6, v2
	v_cvt_pk_bf16_f32 v3, v3, v4
	v_cvt_pk_bf16_f32 v4, v10, v7
	v_cvt_pk_bf16_f32 v5, v8, v5
	global_store_dwordx4 v[18:19], v[2:5], off offset:256
	s_cbranch_vccnz .LBB0_861
	s_andn2_b64 vcc, exec, s[6:7]
	s_cbranch_vccnz .LBB0_860
	s_barrier
	s_branch .LBB0_860
